# v042 + kernarg block cached in v247 lanes at kernel start; all later kernarg s_loads become v_readlane
# speedup vs baseline: 1.0014x; 1.0014x over previous
; #define LAS __attribute__((address_space(3)))
; __global__ void __launch_bounds__(512, 2) fwd_mega(Args a) {
;     extern __shared__ __attribute__((aligned(16))) unsigned char lds_raw[];
;     LAS unsigned char* lds = (LAS unsigned char*)lds_raw;
;     const int tid = threadIdx.x, lane = tid & 63, wave = __builtin_amdgcn_readfirstlane(tid >> 6);
;     const int G = gridDim.x, bx = blockIdx.x;
;     const int gw = bx * 8 + wave, NGW = G * 8, gtid = bx * 512 + tid, NTH = G * 512;
;     ...
;     volatile LAS unsigned* xst = (volatile LAS unsigned*)(lds + XST_OFF);
;     if (tid < 2) xst[tid] = 0u;
;     unsigned* barw = (unsigned*)(a.ws + WS_BAR);
;     __syncthreads();
;     XcdBarrier bar = xcd_barrier_post(barw, xst);
;     {
;         float* cs = (float*)lds_raw; float* red = cs + 4096;
;         for (int u = bx; u < 192; u += G) {
;             const int l = u / 96, cb = u % 96;
;             for (int i = tid; i < 4096; i += 512) { const float v = INF(1)[i]; cs[i] = v / (1.f + __expf(-v)); }
;             __syncthreads();
;             const int kg = tid >> 6, col = tid & 63, j = cb * 64 + col;
;             const float* w = INF(3) + (size_t)l * 1024 * 6144 + (size_t)(kg * 128) * 6144 + j;
;             float a0 = 0.f, a1 = 0.f, a2 = 0.f, a3 = 0.f;
; #pragma unroll 32
;             for (int k = 0; k < 128; ++k) { const float wv = w[(size_t)k * 6144]; const int kk = kg * 128 + k; a0 += cs[kk] * wv; a1 += cs[1024 + kk] * wv; a2 += cs[2048 + kk] * wv; a3 += cs[3072 + kk] * wv; }
;             red[(kg * 4 + 0) * 64 + col] = a0; red[(kg * 4 + 1) * 64 + col] = a1; red[(kg * 4 + 2) * 64 + col] = a2; red[(kg * 4 + 3) * 64 + col] = a3;
;             __syncthreads();
;             if (tid < 256) { const int b = tid >> 6, cc = tid & 63; float s = 0.f;
; #pragma unroll
;                 for (int q = 0; q < 8; ++q) s += red[(q * 4 + b) * 64 + cc];
;                 ((float*)(a.ws + WS_MOD))[(size_t)(l * 4 + b) * 6144 + cb * 64 + cc] = s + INF(4)[l * 6144 + cb * 64 + cc]; }
;             __syncthreads();
_Z8fwd_mega4Args:
	v_mbcnt_lo_u32_b32 v247, -1, 0
	v_mbcnt_hi_u32_b32 v247, -1, v247
	v_lshlrev_b32_e32 v247, 2, v247
	global_load_dword v247, v247, s[0:1]
	s_load_dword s3, s[0:1], 0xe0
	s_add_u32 s4, s0, 0xe0
	v_lshrrev_b32_e32 v1, 6, v0
	s_addc_u32 s5, s1, 0
	v_readfirstlane_b32 s24, v1
	v_writelane_b32 v246, s4, 0
	v_cmp_gt_u32_e32 vcc, 2, v0
	s_nop 0
	v_writelane_b32 v246, s5, 1
	s_and_saveexec_b64 s[4:5], vcc
	v_lshl_add_u32 v2, v0, 2, 0
	v_add_u32_e32 v2, 0x23f00, v2
	v_mov_b32_e32 v3, 0
	ds_write_b32 v2, v3
	s_or_b64 exec, exec, s[4:5]
	s_load_dwordx2 s[26:27], s[0:1], 0xb8
	s_waitcnt lgkmcnt(0)
	s_waitcnt vmcnt(0)
	s_barrier
	s_getreg_b32 s4, hwreg(HW_REG_XCC_ID, 0, 4)
	s_add_u32 s70, s26, 0x700000
	s_addc_u32 s71, s27, 0
	s_and_b32 s33, s4, 15
	v_cmp_eq_u32_e64 s[72:73], 0, v0
	s_and_saveexec_b64 s[4:5], s[72:73]
	s_cbranch_execz .LBB0_5
	s_mov_b64 s[6:7], exec
	v_mbcnt_lo_u32_b32 v2, s6, 0
	v_mbcnt_hi_u32_b32 v2, s7, v2
	v_cmp_eq_u32_e32 vcc, 0, v2
	s_and_b64 s[8:9], exec, vcc
	s_mov_b64 exec, s[8:9]
	s_cbranch_execz .LBB0_5
	s_lshl_b32 s8, s33, 8
	s_bcnt1_i32_b64 s6, s[6:7]
	v_mov_b32_e32 v2, s8
	v_mov_b32_e32 v3, s6
	global_atomic_add v2, v3, s[70:71] offset:1024
.LBB0_5:
	s_or_b64 exec, exec, s[4:5]
	s_cmpk_gt_i32 s2, 0xbf
	v_and_b32_e32 v114, 63, v0
	s_cbranch_scc1 .LBB0_14
	v_readlane_b32 s10, v247, 2
	v_readlane_b32 s11, v247, 3
	v_readlane_b32 s4, v247, 6
	v_readlane_b32 s5, v247, 7
	v_readlane_b32 s6, v247, 8
	v_readlane_b32 s7, v247, 9
	s_nop 4
	s_mov_b64 s[8:9], s[26:27]
	v_mul_u32_u24_e32 v3, 0xc0000, v1
	v_lshlrev_b32_e32 v116, 2, v3
	v_mov_b32_e32 v117, 0
	v_lshl_add_u32 v2, v114, 2, 0
	s_waitcnt lgkmcnt(0)
	v_lshl_add_u64 v[118:119], s[4:5], 0, v[116:117]
	v_lshlrev_b32_e32 v3, 10, v1
	s_movk_i32 s4, 0x100
	v_and_b32_e32 v4, 0xc0, v0
	v_lshlrev_b32_e32 v116, 2, v0
	v_lshl_add_u32 v115, v1, 9, 0
	v_cmp_gt_u32_e64 s[4:5], s4, v0
	v_lshl_add_u32 v130, v4, 2, v2
	v_or_b32_e32 v131, 0xfffffe00, v0
	v_lshl_add_u64 v[120:121], s[10:11], 0, v[116:117]
	v_add_u32_e32 v132, 0, v116
	s_mov_b64 s[10:11], 0x800
	s_movk_i32 s16, 0xdff
	v_mov_b32_e32 v133, 0x1800000
	s_movk_i32 s17, 0x6000
	s_mov_b32 s18, 0xc000
	s_mov_b32 s19, 0x12000
	s_mov_b32 s20, 0x18000
	s_mov_b32 s21, 0x1e000
	s_mov_b32 s22, 0x24000
	s_mov_b32 s23, 0x2a000
	s_mov_b32 s25, 0x30000
	s_mov_b32 s28, 0x36000
	s_mov_b32 s29, 0x3c000
	s_mov_b32 s30, 0x42000
	s_mov_b32 s31, 0x48000
	s_mov_b32 s34, 0x4e000
	s_mov_b32 s35, 0x54000
	s_mov_b32 s36, 0x5a000
	s_mov_b32 s37, 0x60000
	s_mov_b32 s38, 0x66000
	s_mov_b32 s39, 0x6c000
	s_mov_b32 s40, 0x72000
	s_mov_b32 s41, 0x78000
	s_mov_b32 s42, 0x7e000
	s_mov_b32 s43, 0x84000
	s_mov_b32 s44, 0x8a000
	s_mov_b32 s45, 0x90000
	s_mov_b32 s46, 0x96000
	s_mov_b32 s47, 0x9c000
	s_mov_b32 s48, 0xa2000
	s_mov_b32 s49, 0xa8000
	s_mov_b32 s50, 0xae000
	s_mov_b32 s51, 0xb4000
	s_mov_b32 s52, 0xba000
	v_add_u32_e32 v134, v2, v3
	v_lshlrev_b32_e32 v116, 2, v114
	s_mov_b32 s53, s2
	s_branch .LBB0_8

; __global__ void __launch_bounds__(512, 2) fwd_mega(Args a) {
;     ...
;         for (int row = gtid; row < M; row += NTH) {
;             const float p = (float)((const int*)a.in[2])[row];
; #pragma unroll
;             for (int d = 0; d < 8; ++d) { const float ang = p * a.invf[d]; const double rev = (double)ang * 0.15915494309189535; const float f = (float)(rev - rint(rev));
;                 ((float*)(a.ws + WS_ROPE))[(size_t)row * 16 + d] = __builtin_amdgcn_cosf(f); ((float*)(a.ws + WS_ROPE))[(size_t)row * 16 + 8 + d] = __builtin_amdgcn_sinf(f); }
;         }
.LBB0_14:
	v_lshl_or_b32 v2, s2, 9, v0
	s_movk_i32 s4, 0x4000
	v_cmp_gt_i32_e32 vcc, s4, v2
	s_and_saveexec_b64 s[12:13], vcc
	s_cbranch_execz .LBB0_17
	v_readlane_b32 s16, v247, 4
	v_readlane_b32 s17, v247, 5
	s_nop 4
	s_mov_b64 s[18:19], s[26:27]
	v_readlane_b32 s4, v247, 48
	v_readlane_b32 s5, v247, 49
	v_readlane_b32 s6, v247, 50
	v_readlane_b32 s7, v247, 51
	v_readlane_b32 s8, v247, 52
	v_readlane_b32 s9, v247, 53
	v_readlane_b32 s10, v247, 54
	v_readlane_b32 s11, v247, 55
	s_nop 4
	v_ashrrev_i32_e32 v3, 31, v2
	s_lshl_b32 s14, s3, 9
	v_lshlrev_b64 v[6:7], 6, v[2:3]
	s_ashr_i32 s15, s14, 31
	s_waitcnt lgkmcnt(0)
	v_lshl_add_u64 v[6:7], s[18:19], 0, v[6:7]
	s_mov_b64 s[18:19], 0x100000
	s_mov_b32 s22, 0x6dc9c883
	v_lshl_add_u64 v[4:5], v[2:3], 2, s[16:17]
	s_lshl_b64 s[16:17], s[14:15], 2
	v_lshl_add_u64 v[6:7], v[6:7], 0, s[18:19]
	s_lshl_b64 s[18:19], s[14:15], 6
	s_mov_b64 s[20:21], 0
	s_mov_b32 s23, 0x3fc45f30
	s_movk_i32 s15, 0x3fff

; __device__ __forceinline__ void tr_item(const float* W, int N, bf16* WT, int dpitch, int koff, int drow0, int k0, int n0, LAS float* scr, int lane) {
;     float tv[32];
; #pragma unroll
;     for (int i = 0; i < 32; ++i) tv[i] = W[(size_t)(k0 + 2 * i + (lane >> 5)) * N + n0 + (lane & 31)];
; #pragma unroll
;     for (int i = 0; i < 32; ++i) scr[(2 * i + (lane >> 5)) * 33 + (lane & 31)] = tv[i];
;     LDS_WAIT(); asm volatile("" ::: "memory");
;     const int c = lane & 7;
; #pragma unroll
;     for (int j = 0; j < 4; ++j) { const int n = (lane >> 3) + 8 * j; const LAS float* s = scr + (8 * c) * 33 + n;
; __global__ void __launch_bounds__(512, 2) fwd_mega(Args a) {
;     ...
;     auto convert_items = [&](int LL, int lo, int hi, int w0, int nw_, size_t wd_off) __attribute__((always_inline)) {
;         LAS float* scr = (LAS float*)(lds + wave * 16384);
;         for (int it0 = lo + w0; it0 < hi; it0 += nw_) {
;             int it = it0;
;             if (it < 2688) { const int kb = it / 168, nb = it % 168; tr_item(INF(6) + (size_t)LL * D * INC, INC, WSP(WS_WIN), 1024, 0, 32 * nb, 64 * kb, 32 * nb, scr, lane); continue; } it -= 2688;
;             if (it < 512) { const int kb = it / 32, nb = it % 32; tr_item(INF(13) + (size_t)LL * D * D, D, WSP(WS_PAB), 1024, 0, 32 * nb, 64 * kb, 32 * nb, scr, lane); continue; } it -= 512;
;             if (it < 512) { const int kb = it / 32, nb = it % 32; tr_item(INF(12) + (size_t)LL * D * D, D, WSP(WS_PAB), 1024, 0, 1024 + 32 * nb, 64 * kb, 32 * nb, scr, lane); continue; } it -= 512;
;             if (it < 512) { const int kb = it / 32, nb = it % 32; tr_item(INF(14) + (size_t)LL * D * D, D, WSP(WS_WO2), 1024, 0, 32 * nb, 64 * kb, 32 * nb, scr, lane); continue; } it -= 512;
;             if (it < 1408) { const int kb = it / 88, nb = it % 88, n0 = 32 * nb; tr_item(INF(16) + (size_t)LL * D * FF, FF, WSP(WS_WGU), 1024, 0, (n0 >> 7) * 256 + (n0 & 127), 64 * kb, n0, scr, lane); continue; } it -= 1408;
;             if (it < 1408) { const int kb = it / 88, nb = it % 88, n0 = 32 * nb; tr_item(INF(17) + (size_t)LL * D * FF, FF, WSP(WS_WGU), 1024, 0, (n0 >> 7) * 256 + 128 + (n0 & 127), 64 * kb, n0, scr, lane); continue; } it -= 1408;
;             { const int kb = it / 32, nb = it % 32; tr_item(INF(20) + (size_t)LL * FF * D, D, WSP(wd_off), 2816, 0, 32 * nb, 64 * kb, 32 * nb, scr, lane); }
;         }
;     };
.LBB0_17:
	s_or_b64 exec, exec, s[12:13]
	s_lshl_b32 s4, s2, 3
	v_writelane_b32 v246, s4, 2
	s_add_i32 s22, s24, s4
	s_lshl_b32 s4, s24, 14
	s_lshl_b32 s77, s3, 3
	s_add_i32 s4, s4, 0
	s_cmpk_lt_i32 s22, 0x2100
	v_writelane_b32 v246, s4, 3
	s_cselect_b64 s[6:7], -1, 0
	s_mov_b32 s5, 0
	v_writelane_b32 v246, s6, 4
	s_cmpk_gt_i32 s22, 0x20ff
	v_lshrrev_b32_e32 v200, 5, v114
	v_and_b32_e32 v205, 31, v0
	v_lshrrev_b32_e32 v201, 3, v114
	v_lshlrev_b32_e32 v204, 3, v0
	v_writelane_b32 v246, s7, 5
	s_cbranch_scc1 .LBB0_44
	v_readlane_b32 s6, v247, 40
	v_readlane_b32 s7, v247, 41
	s_nop 4
	s_mov_b64 s[8:9], s[26:27]
	v_mov_b32_e32 v3, 0
	v_and_b32_e32 v6, 56, v204
	v_mul_u32_u24_e32 v8, 0x84, v6
	v_lshlrev_b32_e32 v6, 1, v6
	v_mov_b32_e32 v7, v3
	s_waitcnt lgkmcnt(0)
	v_lshl_add_u64 v[26:27], s[8:9], 0, v[6:7]
	v_readlane_b32 s8, v247, 32
	v_readlane_b32 s9, v247, 33
	v_readlane_b32 s10, v247, 34
	v_readlane_b32 s11, v247, 35
	s_nop 4
	v_lshlrev_b32_e32 v2, 2, v205
	v_lshl_add_u64 v[4:5], s[6:7], 0, v[2:3]
	s_mov_b64 s[6:7], 0x2580000
	v_lshl_add_u64 v[6:7], v[26:27], 0, s[6:7]
	v_readlane_b32 s6, v247, 28
	v_readlane_b32 s7, v247, 29
	s_nop 4
	v_readlane_b32 s4, v246, 3
	v_lshlrev_b32_e32 v9, 2, v201
	s_waitcnt lgkmcnt(0)
	v_lshl_add_u64 v[12:13], s[8:9], 0, v[2:3]
	v_add3_u32 v28, s4, v8, v9
	v_lshl_add_u64 v[8:9], s[10:11], 0, v[2:3]
	s_mov_b64 s[10:11], 0x1a80000
	v_lshl_add_u64 v[10:11], v[26:27], 0, s[10:11]
	v_readlane_b32 s12, v247, 12
	v_readlane_b32 s13, v247, 13
	v_readlane_b32 s8, v247, 24
	v_readlane_b32 s9, v247, 25
	v_readlane_b32 s10, v247, 26
	v_readlane_b32 s11, v247, 27
	s_nop 4
	v_lshl_add_u64 v[14:15], s[6:7], 0, v[2:3]
	s_mov_b64 s[6:7], 0x1680000
	v_mul_u32_u24_e32 v1, 0x84, v200
	v_lshl_add_u64 v[16:17], v[26:27], 0, s[6:7]
	s_mov_b64 s[6:7], 0x1280000
	v_add3_u32 v1, s4, v2, v1
	v_lshl_add_u64 v[20:21], v[26:27], 0, s[6:7]
	s_mov_b64 s[6:7], 0x800000
	v_or_b32_e32 v29, 8, v201
	v_or_b32_e32 v30, 16, v201
	v_or_b32_e32 v31, 24, v201
	s_waitcnt lgkmcnt(0)
	v_lshl_add_u64 v[18:19], s[8:9], 0, v[2:3]
	v_lshl_add_u64 v[22:23], s[10:11], 0, v[2:3]
	v_lshl_add_u64 v[24:25], s[12:13], 0, v[2:3]
	v_lshl_add_u64 v[26:27], v[26:27], 0, s[6:7]
	s_lshl_b32 s10, s22, 5
	s_lshl_b32 s11, s77, 5
	s_lshl_b32 s12, s22, 1
	s_lshl_b32 s13, s77, 1
	s_movk_i32 s14, 0x7fff
	s_mov_b32 s15, 0xffff0000
	s_movk_i32 s16, 0x5000
	s_mov_b32 s17, 0xb000
	s_mov_b32 s18, 0x10000
	s_mov_b32 s19, 0x16000
	s_mov_b32 s20, 0x1b000
	s_mov_b32 s21, 0x21000
	s_mov_b32 s23, 0x26000
	s_mov_b32 s24, 0x2c000
	s_mov_b32 s25, 0x31000
	s_mov_b32 s28, 0x37000
	s_mov_b32 s29, 0x3c000
	s_mov_b32 s30, 0x42000
	s_mov_b32 s31, 0x47000
	s_mov_b32 s34, 0x4d000
	s_mov_b32 s35, 0x52000
	s_mov_b32 s36, 0x58000
	s_mov_b32 s37, 0x5d000
	s_mov_b32 s38, 0x63000
	s_mov_b32 s39, 0x68000
	s_mov_b32 s40, 0x6e000
	s_mov_b32 s41, 0x73000
	s_mov_b32 s42, 0x79000
	s_mov_b32 s43, 0x7e000
	s_mov_b32 s44, 0x84000
	s_mov_b32 s45, 0x89000
	s_mov_b32 s46, 0x8f000
	s_mov_b32 s47, 0x94000
	s_mov_b32 s48, 0x9a000
	s_mov_b32 s49, 0x9f000
	s_mov_b32 s50, 0xa5000
	s_mov_b32 s51, 0xaa000
	s_movk_i32 s52, 0x5400
	v_add_u32_e32 v32, 0x400, v1
	v_add_u32_e32 v33, 0x800, v1
	v_add_u32_e32 v34, 0xc00, v1
	v_add_u32_e32 v35, 0x1000, v1
	v_add_u32_e32 v36, 0x1400, v1
	v_add_u32_e32 v37, 0x1800, v1
	v_add_u32_e32 v38, 0x1c00, v1
	s_mov_b32 s53, s22
	s_branch .LBB0_20

; __device__ __forceinline__ unsigned cvt_pk_bf16(float lo, float hi) { unsigned r; asm volatile("v_cvt_pk_bf16_f32 %0, %1, %2" : "=v"(r) : "v"(lo), "v"(hi)); return r; }
; __device__ __forceinline__ void sgu_wfrag_item(const float* Wl, v4u* WF, int item, int lane) {
;     const int g = item / 20, q = item % 20, fr = lane & 15, fq = lane >> 4;
;     int mt = 0, ks = 0, c = 0;
;     for (int m = 0; m < 8; ++m) for (int k = 0; k <= (m >> 1); ++k) { if (c == q) { mt = m; ks = k; } ++c; }
;     const int t = 16 * mt + fr, sb = 32 * ks + 8 * fq;
;     const float* p = Wl + ((size_t)g * 128 + t) * 128 + sb;
;     const f32x4 wa = *(const f32x4*)p, wb = *(const f32x4*)(p + 4);
;     v4u ww;
;     ww.x = cvt_pk_bf16(sb + 0 <= t ? wa.x : 0.f, sb + 1 <= t ? wa.y : 0.f); ww.y = cvt_pk_bf16(sb + 2 <= t ? wa.z : 0.f, sb + 3 <= t ? wa.w : 0.f);
;     ww.z = cvt_pk_bf16(sb + 4 <= t ? wb.x : 0.f, sb + 5 <= t ? wb.y : 0.f); ww.w = cvt_pk_bf16(sb + 6 <= t ? wb.z : 0.f, sb + 7 <= t ? wb.w : 0.f);
;     WF[(size_t)item * 64 + lane] = ww;
; }
; __global__ void __launch_bounds__(512, 2) fwd_mega(Args a) {
;     ...
;             for (int it = gw; it < 160; it += NGW) sgu_wfrag_item(INF(10), (v4u*)(a.ws + WS_WF), it, lane);
.LBB0_44:
	s_cmpk_lt_i32 s22, 0xa0
	s_cselect_b64 s[4:5], -1, 0
	v_writelane_b32 v246, s4, 6
	s_cmpk_gt_i32 s22, 0x9f
	v_and_b32_e32 v202, 15, v0
	v_lshrrev_b32_e32 v203, 1, v0
	v_lshlrev_b32_e32 v172, 4, v114
	v_writelane_b32 v246, s5, 7
	s_cbranch_scc1 .LBB0_47
	s_mov_b64 s[4:5], s[26:27]
	v_readlane_b32 s18, v247, 20
	v_readlane_b32 s19, v247, 21
	s_nop 4
	v_mov_b32_e32 v3, 0
	v_mov_b32_e32 v173, v3
	v_and_b32_e32 v1, 24, v203
	s_waitcnt lgkmcnt(0)
	v_lshl_add_u64 v[4:5], s[4:5], 0, v[172:173]
	s_mov_b64 s[4:5], 0x680000
	v_lshl_add_u64 v[4:5], v[4:5], 0, s[4:5]
	s_mov_b32 s20, s22

; __device__ __forceinline__ unsigned cvt_pk_bf16(float lo, float hi) { unsigned r; asm volatile("v_cvt_pk_bf16_f32 %0, %1, %2" : "=v"(r) : "v"(lo), "v"(hi)); return r; }
; __global__ void __launch_bounds__(512, 2) fwd_mega(Args a) {
;     ...
;             const float* xin = (l == 0) ? INF(0) : a.out; const float* nw = INF(5) + l * D; const float* ml = (const float*)(a.ws + WS_MOD) + (size_t)l * 4 * 6144;
;             for (int m0 = gw; m0 < M; m0 += 2 * NGW) {
;                 const int m1 = m0 + NGW; const bool has1 = m1 < M; const int m1c = has1 ? m1 : m0;
;                 const f32x4* xr0 = (const f32x4*)(xin + (size_t)m0 * D) + lane; const f32x4* xr1 = (const f32x4*)(xin + (size_t)m1c * D) + lane;
;                 f32x4 v0[4], v1[4]; float ss0 = 0.f, ss1 = 0.f;
; #pragma unroll
;                 for (int j = 0; j < 4; ++j) { v0[j] = xr0[64 * j]; v1[j] = xr1[64 * j]; }
; #pragma unroll
;                 for (int j = 0; j < 4; ++j) { ss0 += (v0[j].x * v0[j].x + v0[j].y * v0[j].y) + (v0[j].z * v0[j].z + v0[j].w * v0[j].w); ss1 += (v1[j].x * v1[j].x + v1[j].y * v1[j].y) + (v1[j].z * v1[j].z + v1[j].w * v1[j].w); }
;                 const float rstd0 = rsqrtf(wave_sum(ss0) * (1.f / D) + 1e-6f), rstd1 = rsqrtf(wave_sum(ss1) * (1.f / D) + 1e-6f);
;                 const int b0 = m0 >> 12, b1 = m1c >> 12;
;                 v2u* o0 = (v2u*)(WSP(WS_H) + (size_t)m0 * D) + lane; v2u* o1 = (v2u*)(WSP(WS_H) + (size_t)m1c * D) + lane;
; #pragma unroll
;                 for (int j = 0; j < 4; ++j) { const int col = 4 * lane + 256 * j; const f32x4 wv = *(const f32x4*)(nw + col);
;                     const f32x4 sh0 = *(const f32x4*)(ml + (size_t)b0 * 6144 + col), sc0 = *(const f32x4*)(ml + (size_t)b0 * 6144 + 1024 + col);
;                     const f32x4 sh1 = *(const f32x4*)(ml + (size_t)b1 * 6144 + col), sc1 = *(const f32x4*)(ml + (size_t)b1 * 6144 + 1024 + col);
;                     const f32x4 y0 = (v0[j] * rstd0) * wv * (sc0 + 1.0f) + sh0, y1 = (v1[j] * rstd1) * wv * (sc1 + 1.0f) + sh1;
;                     v2u w0; w0.x = cvt_pk_bf16(y0.x, y0.y); w0.y = cvt_pk_bf16(y0.z, y0.w); o0[64 * j] = w0;
;                     if (has1) { v2u w1; w1.x = cvt_pk_bf16(y1.x, y1.y); w1.y = cvt_pk_bf16(y1.z, y1.w); o1[64 * j] = w1; } }
;             }
.LBB0_99:
	s_or_b64 exec, exec, s[4:5]
	s_cmpk_gt_i32 s22, 0x3fff
	s_waitcnt lgkmcnt(0)
	v_mbcnt_lo_u32_b32 v1, -1, 0
	s_barrier
	s_cbranch_scc1 .LBB0_110
	v_mbcnt_hi_u32_b32 v2, -1, v1
	v_and_b32_e32 v3, 64, v2
	v_add_u32_e32 v3, 64, v3
	v_xor_b32_e32 v4, 1, v2
	v_cmp_lt_i32_e32 vcc, v4, v3
	s_mov_b64 s[6:7], s[26:27]
	v_readlane_b32 s4, v247, 0
	v_readlane_b32 s5, v247, 1
	v_readlane_b32 s8, v247, 10
	v_readlane_b32 s9, v247, 11
	s_nop 4
	v_cndmask_b32_e32 v4, v2, v4, vcc
	v_lshlrev_b32_e32 v57, 2, v4
	v_xor_b32_e32 v4, 2, v2
	v_cmp_lt_i32_e32 vcc, v4, v3
	v_mov_b32_e32 v173, 0
	s_ashr_i32 s23, s22, 31
	v_cndmask_b32_e32 v4, v2, v4, vcc
	v_lshlrev_b32_e32 v66, 2, v4
	v_xor_b32_e32 v4, 4, v2
	v_cmp_lt_i32_e32 vcc, v4, v3
	s_waitcnt lgkmcnt(0)
	v_lshl_add_u64 v[50:51], s[8:9], 0, v[172:173]
	s_lshl_b32 s8, s3, 4
	v_cndmask_b32_e32 v4, v2, v4, vcc
	v_lshlrev_b32_e32 v67, 2, v4
	v_xor_b32_e32 v4, 8, v2
	v_cmp_lt_i32_e32 vcc, v4, v3
	s_lshl_b64 s[10:11], s[22:23], 12
	v_lshl_add_u64 v[46:47], s[4:5], 0, v[172:173]
	v_cndmask_b32_e32 v4, v2, v4, vcc
	v_lshlrev_b32_e32 v68, 2, v4
	v_xor_b32_e32 v4, 16, v2
	v_cmp_lt_i32_e32 vcc, v4, v3
	s_add_u32 s4, s4, s10
	s_addc_u32 s5, s5, s11
	v_cndmask_b32_e32 v4, v2, v4, vcc
	v_lshlrev_b32_e32 v69, 2, v4
	v_xor_b32_e32 v4, 32, v2
	v_cmp_lt_i32_e32 vcc, v4, v3
	s_ashr_i32 s9, s8, 31
	v_mov_b32_e32 v3, v173
	v_cndmask_b32_e32 v2, v2, v4, vcc
	v_lshlrev_b32_e32 v70, 2, v2
	v_lshlrev_b32_e32 v2, 3, v114
	v_lshl_add_u64 v[52:53], s[4:5], 0, v[172:173]
	s_lshl_b64 s[10:11], s[8:9], 12
	s_lshl_b64 s[4:5], s[22:23], 11
	v_lshl_add_u64 v[4:5], s[6:7], 0, v[2:3]
	s_mov_b64 s[12:13], 0x2b00000
	s_add_u32 s4, s6, s4
	v_lshl_add_u64 v[48:49], v[4:5], 0, s[12:13]
	v_lshlrev_b32_e32 v4, 2, v114
	s_addc_u32 s5, s7, s5
	v_or_b32_e32 v6, 0x100, v4
	v_or_b32_e32 v8, 0x200, v4
	v_or_b32_e32 v10, 0x300, v4
	v_lshl_add_u64 v[2:3], s[4:5], 0, v[2:3]
	v_lshl_add_u64 v[54:55], v[2:3], 0, s[12:13]
	s_lshl_b64 s[12:13], s[8:9], 11
	s_mov_b32 s14, 0x3a800000
	v_mov_b32_e32 v56, 0x358637bd
	s_mov_b32 s9, 0x800000
	v_lshlrev_b32_e32 v58, 2, v4
	v_mov_b32_e32 v59, v173
	v_lshlrev_b32_e32 v71, 2, v6
	v_lshlrev_b32_e32 v72, 2, v8
	v_lshlrev_b32_e32 v73, 2, v10
	s_mov_b32 s15, s22
	s_branch .LBB0_102

; #define LAS __attribute__((address_space(3)))
; __device__ __forceinline__ void attn_unit(LAS unsigned char* lds, bf16* Q, const bf16* Kg, const bf16* Vg, const float* snk, int unit, int tid) {
;     const int lane = tid & 63, wave = tid >> 6, fr = lane & 15, fq = lane >> 4;
;     const int b = unit >> 6, n = (unit >> 1) & 31, h = unit & 1, r0 = b * SEQ + n * 128, hq = 8 * h + wave;
;     const v4u zero4 = {0u, 0u, 0u, 0u};
;     bf16* qbase = Q + (size_t)(r0 + fr) * 1024 + hq * 64;
;     bf16x8_t qf[8][2];
; #pragma unroll
;     for (int mt = 0; mt < 8; ++mt) { qf[mt][0] = *(const bf16x8_t*)(qbase + (size_t)mt * 16 * 1024 + 8 * fq); qf[mt][1] = *(const bf16x8_t*)(qbase + (size_t)mt * 16 * 1024 + 32 + 8 * fq); }
; #pragma unroll
;     for (int i = 0; i < 4; ++i) { const int idx = tid + 512 * i, j = idx >> 3, c = idx & 7, p = n * 128 - 128 + j;
;         v4u w = zero4; if (p >= 0) w = *(const v4u*)(Kg + (size_t)(b * SEQ + p) * 128 + h * 64 + c * 8);
;         *(LAS v4u*)(lds + j * ATT_KP + c * 16) = w; }
; #pragma unroll
;     for (int i = 0; i < 2; ++i) { const int idx = tid + 512 * i, j = (idx >> 3) * 2, c = idx & 7, p = n * 128 - 128 + j;
;         v4u w0 = zero4, w1 = zero4;
;         if (p >= 0) { w0 = *(const v4u*)(Vg + (size_t)(b * SEQ + p) * 128 + h * 64 + c * 8); w1 = *(const v4u*)(Vg + (size_t)(b * SEQ + p + 1) * 128 + h * 64 + c * 8); }
;         const unsigned A0[4] = {w0.x, w0.y, w0.z, w0.w}, A1[4] = {w1.x, w1.y, w1.z, w1.w};
; #pragma unroll
;         for (int e = 0; e < 8; ++e) { const unsigned lo = (e & 1) ? (A0[e >> 1] >> 16) : (A0[e >> 1] & 0xffffu), hi = (e & 1) ? (A1[e >> 1] & 0xffff0000u) : (A1[e >> 1] << 16);
;             *(LAS unsigned*)(lds + ATT_VOFF + (8 * c + e) * ATT_VP + j * 2) = lo | hi; } }
;     __syncthreads();
;     const float sink = snk[hq] * 1.4426950408889634f;
;     bool lo_ok[4];
; #pragma unroll
; __global__ void __launch_bounds__(512, 2) fwd_mega(Args a) {
;     ...
;         {
;             int tid_ = threadIdx.x; asm volatile("" : "+v"(tid_));
;             for (int it = bx; it < 512; it += G) {
;                 if (it < 256) attn_unit(lds, WSP(WS_Q), WSP(WS_K), WSP(WS_V), INF(7) + l * 16, it, tid_);
;                 else sgu_unit(lds, WSP(WS_U), WSP(WS_VS), (const float*)(a.ws + WS_SGS), INF(8) + l * 1024, INF(9) + l * 1024, (const v4u*)(a.ws + WS_WF), INF(11) + l * 8 * 128, it - 256, tid_);
;             }
.LBB0_491:
	s_or_b64 exec, exec, s[4:5]
	s_cmpk_lt_i32 s2, 0x200
	s_cselect_b64 s[4:5], -1, 0
	v_mov_b32_e32 v161, v0
	v_writelane_b32 v246, s4, 18
	s_cmpk_gt_i32 s2, 0x1ff
	s_waitcnt lgkmcnt(0)
	s_barrier
	v_writelane_b32 v246, s5, 19
	s_cbranch_scc1 .LBB0_512
	s_mov_b64 s[14:15], s[26:27]
	v_readlane_b32 s42, v247, 22
	v_readlane_b32 s43, v247, 23
	s_nop 4
	v_and_b32_e32 v6, 7, v161
	v_add_u32_e32 v8, 0x200, v161
	v_lshlrev_b32_e32 v170, 3, v6
	v_mul_u32_u24_e32 v10, 0x110, v6
	v_bfe_u32 v15, v161, 4, 2
	v_lshlrev_b32_e32 v4, 4, v6
	s_waitcnt vmcnt(1)
	v_mul_u32_u24_e32 v20, 0x1080, v6
	v_ashrrev_i32_e32 v6, 2, v8
	v_ashrrev_i32_e32 v169, 6, v161
	s_movk_i32 s6, 0x4400
	v_add_u32_e32 v9, 0x400, v161
	v_and_b32_e32 v177, -2, v6
	v_lshlrev_b32_e32 v6, 2, v15
	s_waitcnt lgkmcnt(0)
	s_add_u32 s48, s14, 0x4b00000
	v_and_b32_e32 v3, 63, v161
	v_and_b32_e32 v163, 15, v161
	v_mul_lo_u32 v5, v169, s6
	v_ashrrev_i32_e32 v173, 3, v8
	v_ashrrev_i32_e32 v174, 3, v9
	v_add_u32_e32 v9, 0x600, v161
	v_or_b32_e32 v8, 2, v6
	s_addc_u32 s49, s15, 0
	v_mov_b32_e32 v147, 0
	v_ashrrev_i32_e32 v175, 3, v9
	v_ashrrev_i32_e32 v9, 2, v161
	v_cmp_gt_u32_e64 s[10:11], v8, v163
	v_or_b32_e32 v8, 3, v6
	v_lshlrev_b32_e32 v146, 4, v3
	s_add_u32 s52, s14, 0xf400000
	v_add_u32_e32 v3, 0, v5
	v_lshrrev_b32_e32 v5, 1, v161
	v_bfe_u32 v2, v161, 3, 3
	v_and_b32_e32 v176, -2, v9
	v_cmp_gt_u32_e64 s[12:13], v8, v163
	v_lshl_add_u64 v[8:9], s[14:15], 0, v[146:147]
	s_mov_b64 s[16:17], 0x680000
	s_addc_u32 s53, s15, 0
	v_and_b32_e32 v146, 24, v5
	v_lshlrev_b32_e32 v167, 3, v161
	v_lshlrev_b32_e32 v7, 11, v2
	v_lshlrev_b32_e32 v11, 2, v2
	v_lshlrev_b32_e32 v12, 4, v2
	v_bfe_u32 v2, v161, 3, 1
	v_lshl_add_u64 v[148:149], v[8:9], 0, s[16:17]
	v_lshl_add_u64 v[8:9], s[14:15], 0, v[146:147]
	s_mov_b64 s[16:17], 0x9300000
	s_add_u32 s56, s14, 0x6b00000
	v_mov_b32_e32 v5, v147
	v_and_or_b32 v2, v167, 56, v2
	v_readlane_b32 s28, v247, 14
	v_readlane_b32 s29, v247, 15
	v_readlane_b32 s30, v247, 16
	v_readlane_b32 s31, v247, 17
	v_readlane_b32 s50, v247, 18
	v_readlane_b32 s51, v247, 19
	s_nop 4
	v_lshl_add_u64 v[150:151], v[8:9], 0, s[16:17]
	s_addc_u32 s57, s15, 0
	v_add_u32_e32 v8, 0, v4
	v_lshl_add_u64 v[4:5], s[14:15], 0, v[4:5]
	s_mov_b64 s[14:15], 0x8b00000
	v_mul_u32_u24_e32 v14, 0x110, v2
	v_lshlrev_b32_e32 v2, 3, v15
	v_lshl_add_u64 v[152:153], v[4:5], 0, s[14:15]
	s_mov_b64 s[14:15], 0x8f00000
	v_lshl_add_u32 v9, v15, 4, 0
	v_and_b32_e32 v13, 48, v161
	v_ashrrev_i32_e32 v171, 3, v161
	s_movk_i32 s18, 0x90
	v_add3_u32 v178, v3, v10, v11
	v_lshl_add_u64 v[154:155], v[4:5], 0, s[14:15]
	v_sub_u32_e32 v10, v9, v2
	s_movk_i32 s14, 0x210
	s_movk_i32 s4, 0x80
	v_mul_lo_u32 v16, v171, s18
	v_mul_lo_u32 v17, v173, s18
	v_mul_lo_u32 v18, v174, s18
	v_mul_lo_u32 v19, v175, s18
	v_add_u32_e32 v3, v3, v13
	v_lshl_add_u32 v4, v176, 1, 0
	v_lshl_add_u32 v5, v177, 1, 0
	v_mad_u32_u24 v180, v163, s14, v10
	s_lshl_b32 s14, s2, 2
	v_ashrrev_i32_e32 v165, 7, v161
	v_cmp_gt_i32_e64 s[4:5], s4, v161
	v_and_b32_e32 v168, 64, v161
	v_cmp_gt_u32_e64 s[6:7], v6, v163
	v_cmp_lt_u32_e64 s[8:9], v6, v163
	s_mov_b32 s55, 0
	v_mad_u32_u24 v179, v163, s18, v9
	s_add_i32 s23, s14, 0xfffffc00
	s_lshl_b32 s24, s3, 2
	s_lshl_b32 s25, s2, 6
	s_lshl_b32 s34, s3, 6
	s_movk_i32 s35, 0x1000
	s_movk_i32 s36, 0x2000
	s_movk_i32 s37, 0x3000
	s_movk_i32 s38, 0x4000
	s_mov_b32 s58, 0x3a800000
	s_mov_b32 s39, 0x800000
	v_lshlrev_b32_e32 v181, 1, v7
	s_mov_b32 s40, 0x8000
	s_mov_b32 s41, 0x10000
	s_mov_b32 s44, 0x18000
	s_mov_b32 s45, 0x20000
	s_mov_b32 s46, 0x28000
	s_mov_b32 s47, 0x30000
	s_mov_b32 s59, 0x38000
	v_add_u32_e32 v182, 0, v12
	s_mov_b32 s60, 0xffff0000
	v_add_u32_e32 v183, v3, v14
	v_lshlrev_b32_e32 v146, 1, v2
	v_add_u32_e32 v184, v8, v16
	v_add_u32_e32 v185, v8, v17
	v_add_u32_e32 v186, v8, v18
	v_add_u32_e32 v187, v8, v19
	s_mov_b32 s61, 0xffff
	v_add_u32_e32 v188, v4, v20
	v_add_u32_e32 v189, v5, v20
	s_mov_b32 s62, 0x3fb8aa3b
	v_lshlrev_b32_e32 v156, 1, v6
	v_mbcnt_hi_u32_b32 v190, -1, v1
	v_mov_b32_e32 v191, 0xff800000
	s_mov_b32 s63, s2
	s_branch .LBB0_495

; template <class Epi, class Sched, bool ALIGN_EPI = false, bool SP2 = false, bool PAIR_ACC = false>
; __device__ __forceinline__ void gemm_phase(PG8_LAS unsigned char* lds, const Gemm g, const Sched& S, const Epi& E) {
;     ...
;     const int tid = tid_, wid = __builtin_amdgcn_readfirstlane(tid >> 6), lane = tid & 63, wr = wid >> 2, wc = wid & 3, fr = lane & 15, fq = lane >> 4;
;     const int K = g.K, nt = K / BK;
;     unsigned voffA[2], voffB[2];
; #pragma unroll
;     for (int i = 0; i < 2; ++i) { int R, C; stage_rc(tid * 16 + i * 8192, R, C); const int Rb = Epi::PERM ? ((R & ~31) + perm32(R & 31)) : R;
;         voffA[i] = (unsigned)(R * K + C) * 2u; voffB[i] = (unsigned)(Rb * K + C) * 2u; }
;     const size_t kstep = (size_t)(BK * 2);
;     const size_t hstep = (size_t)HALF * K * 2;
;     const size_t tstep = 2 * hstep;
;     const unsigned ldsw = (unsigned)wid * 1024u;
;     const int aoff = lds_byte(wr * 64 + fr, fq * 8), boff = lds_byte(wc * 32 + fr, fq * 8);
;     ...
;     Unit cur, nxt; int ui = 0;
;     if (!S.next(0, cur)) return;
;     f32x4 acc[2][2][4][2];
; #pragma unroll
;     for (int a = 0; a < 2; ++a)
; #pragma unroll
;         for (int b = 0; b < 2; ++b)
; #pragma unroll
;             for (int m = 0; m < 4; ++m)
; #pragma unroll
;                 for (int n = 0; n < 2; ++n) acc[a][b][m][n] = (f32x4){0.f, 0.f, 0.f, 0.f};
;     bf16x8 At[4][2], B0[2][2], B1[2][2];
;     const char* cA = (const char*)g.A + (size_t)cur.pm * tstep + (size_t)(cur.pn / g.a_div) * g.a_sel; const char* cB = (const char*)g.Bt + (size_t)cur.pn * tstep;
;     S.a_ready(cur);
;     if constexpr (SP2) {
;         PG8_STAGE(PG8_SB(0, 0), cB, voffB); PG8_STAGE(PG8_SB(0, 1), cB + hstep, voffB); PG8_STAGE(PG8_SA(0, 0), cA, voffA); PG8_STAGE(PG8_SA(0, 1), cA + hstep, voffA);
;         if (wr == 1) PG8_BAR;
; __global__ void __launch_bounds__(512, 2) fwd_mega(Args a) {
;     ...
;         {
;             pg8::Gemm g{WSP(WS_MG), WSP(WS_WO2), M, D, D, 1 << 20, 0}; pg8::StaticOrder S; S.init(M, D, G, bx);
;             const float* ml = (const float*)(a.ws + WS_MOD) + (size_t)l * 4 * 6144;
;     ...
;             if constexpr (l == 0) {
;                 pg8::EpiResidNorm<false, false> E{INF(0), WSP(WS_XMID), ml + 2048, WSP(WS_H2), INF(15) + l * D, ml, 3072, 4096, st};
;                 pg8::gemm_phase<pg8::EpiResidNorm<false, false>, pg8::StaticOrder, false, true>(lds, g, S, E);
.LBB0_715:
	v_ashrrev_i32_e32 v3, 31, v166
	v_lshrrev_b32_e32 v3, 26, v3
	v_add_u32_e32 v3, v166, v3
	v_ashrrev_i32_e32 v10, 6, v3
	v_bfe_i32 v3, v166, 27, 1
	v_lshlrev_b32_e32 v2, 4, v166
	v_lshrrev_b32_e32 v3, 22, v3
	v_add_u32_e32 v3, v2, v3
	v_and_b32_e32 v3, 0xfffffc00, v3
	v_sub_u32_e32 v3, v2, v3
	v_lshrrev_b32_e32 v4, 4, v3
	v_bitop3_b32 v3, v4, v3, 32 bitop3:0x6c
	v_ashrrev_i32_e32 v5, 31, v3
	v_lshrrev_b32_e32 v5, 26, v5
	v_add_u32_e32 v5, v3, v5
	v_lshlrev_b32_e32 v4, 3, v10
	v_ashrrev_i32_e32 v11, 6, v5
	v_and_b32_e32 v5, 0xc0, v5
	v_and_b32_e32 v4, -16, v4
	v_sub_u32_e32 v3, v3, v5
	v_mov_b32_e32 v5, 1
	v_add_u32_e32 v4, v11, v4
	v_ashrrev_i16_sdwa v3, v5, sext(v3) dst_sel:DWORD dst_unused:UNUSED_PAD src0_sel:DWORD src1_sel:BYTE_0
	v_lshlrev_b32_e32 v6, 5, v10
	v_bfe_i32 v12, v3, 0, 16
	v_lshlrev_b32_e32 v3, 1, v4
	v_lshrrev_b32_e32 v7, 2, v4
	v_and_b32_e32 v8, 3, v11
	s_mov_b32 s7, 0x1fffe0
	v_and_b32_e32 v6, 32, v6
	v_and_b32_e32 v3, 24, v3
	v_and_b32_e32 v7, 4, v7
	v_and_or_b32 v8, v4, s7, v8
	v_or3_b32 v3, v8, v7, v3
	v_add_lshl_u32 v6, v6, v12, 1
	v_add_u32_e32 v2, 0x2000, v2
	v_lshl_add_u32 v132, v3, 11, v6
	v_ashrrev_i32_e32 v3, 31, v2
	v_lshrrev_b32_e32 v3, 22, v3
	v_add_u32_e32 v3, v2, v3
	v_ashrrev_i32_e32 v13, 10, v3
	v_mul_i32_i24_e32 v3, 0x400, v13
	v_sub_u32_e32 v2, v2, v3
	s_ashr_i32 s6, s8, 3
	v_lshrrev_b32_e32 v3, 4, v2
	s_waitcnt lgkmcnt(0)
	s_add_u32 s25, s12, 0x2b00000
	v_bitop3_b32 v2, v3, v2, 32 bitop3:0x6c
	s_addc_u32 s34, s13, 0
	v_lshl_add_u32 v130, v4, 11, v6
	v_ashrrev_i32_e32 v4, 31, v2
	s_add_u32 s35, s12, 0x1680000
	v_lshrrev_b32_e32 v4, 26, v4
	s_addc_u32 s36, s13, 0
	v_add_u32_e32 v4, v2, v4
	s_add_i32 s5, s5, s6
	v_lshlrev_b32_e32 v3, 3, v13
	v_ashrrev_i32_e32 v14, 6, v4
	v_and_b32_e32 v4, 0xc0, v4
	s_ashr_i32 s6, s5, 31
	v_and_b32_e32 v3, -16, v3
	v_sub_u32_e32 v2, v2, v4
	s_lshr_b32 s6, s6, 27
	v_add_u32_e32 v3, v14, v3
	v_ashrrev_i16_sdwa v2, v5, sext(v2) dst_sel:DWORD dst_unused:UNUSED_PAD src0_sel:DWORD src1_sel:BYTE_0
	v_and_b32_e32 v5, 3, v14
	s_add_i32 s6, s5, s6
	v_and_or_b32 v5, v3, s7, v5
	s_ashr_i32 s7, s6, 5
	s_andn2_b32 s6, s6, 31
	s_sub_i32 s5, s5, s6
	s_bfe_i32 s6, s5, 0x80000
	s_bfe_u32 s6, s6, 0x3000c
	s_add_i32 s8, s5, s6
	s_bfe_i32 s6, s8, 0x80000
	s_and_b32 s8, s8, 0xf8
	s_sub_i32 s5, s5, s8
	s_lshl_b32 s7, s7, 3
	s_sext_i32_i16 s6, s6
	s_sext_i32_i8 s5, s5
	s_lshr_b32 s6, s6, 3
	s_add_i32 s16, s7, s5
	s_ashr_i32 s11, s4, 6
	s_ashr_i32 s17, s16, 31
	s_bfe_i64 s[14:15], s[6:7], 0x100000
	s_ashr_i32 s23, s4, 8
	s_lshl_b32 s37, s11, 10
	s_lshl_b64 s[8:9], s[16:17], 19
	s_lshl_b64 s[14:15], s[14:15], 19
	s_add_u32 s52, s35, s14
	v_lshlrev_b32_e32 v6, 5, v13
	v_bfe_i32 v15, v2, 0, 16
	v_lshlrev_b32_e32 v2, 1, v3
	v_lshrrev_b32_e32 v4, 2, v3
	s_addc_u32 s53, s36, s15
	s_add_i32 s40, s37, 0
	v_and_b32_e32 v6, 32, v6
	v_and_b32_e32 v2, 24, v2
	v_and_b32_e32 v4, 4, v4
	s_add_i32 m0, s40, 0x10000
	v_or3_b32 v2, v5, v4, v2
	v_add_lshl_u32 v4, v6, v15, 1
	global_load_lds_dwordx4 v132, s[52:53]
	s_add_i32 m0, s40, 0x12000
	v_lshl_add_u32 v136, v2, 11, v4
	s_add_u32 s14, s52, 0x40000
	global_load_lds_dwordx4 v136, s[52:53]
	s_addc_u32 s15, s53, 0
	s_add_i32 m0, s40, 0x14000
	v_lshl_add_u32 v134, v3, 11, v4
	global_load_lds_dwordx4 v132, s[14:15]
	s_add_i32 m0, s40, 0x16000
	s_add_u32 s20, s25, s8
	s_addc_u32 s21, s34, s9
	s_add_i32 s41, s40, 0x2000
	global_load_lds_dwordx4 v136, s[14:15]
	s_mov_b32 m0, s40
	s_add_u32 s8, s20, 0x40000
	global_load_lds_dwordx4 v130, s[20:21]
	s_mov_b32 m0, s41
	s_addc_u32 s9, s21, 0
	s_add_i32 s44, s40, 0x4000
	global_load_lds_dwordx4 v134, s[20:21]
	s_mov_b32 m0, s44
	s_add_i32 s45, s40, 0x6000
	global_load_lds_dwordx4 v130, s[8:9]
	s_mov_b32 m0, s45
	v_mov_b32_e32 v133, 0
	global_load_lds_dwordx4 v134, s[8:9]
	v_readlane_b32 s18, v247, 0
	v_readlane_b32 s19, v247, 1
	v_readlane_b32 s14, v247, 30
	v_readlane_b32 s15, v247, 31
	s_nop 4
	v_mov_b32_e32 v137, v133
	v_mov_b32_e32 v131, v133
	v_mov_b32_e32 v135, v133
	s_mov_b32 s46, 0
	v_lshl_add_u64 v[8:9], s[52:53], 0, v[132:133]
	v_lshl_add_u64 v[6:7], s[52:53], 0, v[136:137]
	v_lshl_add_u64 v[4:5], s[20:21], 0, v[130:131]
	s_cmp_lg_u32 s23, 1
	v_lshl_add_u64 v[2:3], s[20:21], 0, v[134:135]
	s_cbranch_scc1 .LBB0_717
	s_barrier

; #define PG8_BAR __builtin_amdgcn_s_barrier()
; template <class Epi, class Sched, bool ALIGN_EPI = false, bool SP2 = false, bool PAIR_ACC = false>
; __device__ __forceinline__ void gemm_phase(PG8_LAS unsigned char* lds, const Gemm g, const Sched& S, const Epi& E) {
;     ...
;     const int tid = tid_, wid = __builtin_amdgcn_readfirstlane(tid >> 6), lane = tid & 63, wr = wid >> 2, wc = wid & 3, fr = lane & 15, fq = lane >> 4;
;     const int K = g.K, nt = K / BK;
;     unsigned voffA[2], voffB[2];
; #pragma unroll
;     for (int i = 0; i < 2; ++i) { int R, C; stage_rc(tid * 16 + i * 8192, R, C); const int Rb = Epi::PERM ? ((R & ~31) + perm32(R & 31)) : R;
;         voffA[i] = (unsigned)(R * K + C) * 2u; voffB[i] = (unsigned)(Rb * K + C) * 2u; }
;     const size_t kstep = (size_t)(BK * 2);
;     const size_t hstep = (size_t)HALF * K * 2;
;     const size_t tstep = 2 * hstep;
;     const unsigned ldsw = (unsigned)wid * 1024u;
;     const int aoff = lds_byte(wr * 64 + fr, fq * 8), boff = lds_byte(wc * 32 + fr, fq * 8);
;     ...
;     Unit cur, nxt; int ui = 0;
;     if (!S.next(0, cur)) return;
;     f32x4 acc[2][2][4][2];
; #pragma unroll
;     for (int a = 0; a < 2; ++a)
; #pragma unroll
;         for (int b = 0; b < 2; ++b)
; #pragma unroll
;             for (int m = 0; m < 4; ++m)
; #pragma unroll
;                 for (int n = 0; n < 2; ++n) acc[a][b][m][n] = (f32x4){0.f, 0.f, 0.f, 0.f};
;     bf16x8 At[4][2], B0[2][2], B1[2][2];
;     const char* cA = (const char*)g.A + (size_t)cur.pm * tstep + (size_t)(cur.pn / g.a_div) * g.a_sel; const char* cB = (const char*)g.Bt + (size_t)cur.pn * tstep;
;     S.a_ready(cur);
;     if constexpr (SP2) {
;         PG8_STAGE(PG8_SB(0, 0), cB, voffB); PG8_STAGE(PG8_SB(0, 1), cB + hstep, voffB); PG8_STAGE(PG8_SA(0, 0), cA, voffA); PG8_STAGE(PG8_SA(0, 1), cA + hstep, voffA);
;         if (wr == 1) PG8_BAR;
;         PG8_WAIT_V(2); PG8_BAR;
; __global__ void __launch_bounds__(512, 2) fwd_mega(Args a) {
;     ...
;         {
;             pg8::Gemm g{WSP(WS_H2), WSP(WS_WGU), M, 2 * FF, D, 1 << 20, 0}; pg8::StaticOrder S; S.init(M, 2 * FF, G, bx);
;             pg8::EpiGUConv E{WSP(WS_ACT), (float*)(a.ws + WS_RAWA), (float*)(a.ws + WS_RAWU), (float*)(a.ws + WS_TAILA), INF(18) + (size_t)l * 3 * FF, INF(19) + (size_t)l * FF, lds + XCH_OFF};
;             pg8::gemm_phase<pg8::EpiGUConv, pg8::StaticOrder, true, true>(lds, g, S, E);
.LBB0_825:
	s_or_b64 exec, exec, s[6:7]
	s_cmpk_lt_i32 s2, 0x580
	s_cselect_b64 s[4:5], -1, 0
	v_writelane_b32 v246, s4, 16
	v_mov_b32_e32 v13, v0
	s_waitcnt lgkmcnt(0)
	v_writelane_b32 v246, s5, 17
	s_barrier
	s_cmpk_gt_i32 s2, 0x57f
	v_readfirstlane_b32 s9, v13
	v_writelane_b32 v246, s74, 14
	s_nop 1
	v_writelane_b32 v246, s75, 15
	s_cbranch_scc1 .LBB0_850
	v_lshlrev_b32_e32 v2, 4, v13
	v_add_u32_e32 v3, 0x2000, v2
	v_ashrrev_i32_e32 v4, 31, v3
	v_lshrrev_b32_e32 v4, 22, v4
	v_add_u32_e32 v4, v3, v4
	v_ashrrev_i32_e32 v10, 10, v4
	v_mul_i32_i24_e32 v4, 0x400, v10
	v_sub_u32_e32 v3, v3, v4
	v_lshrrev_b32_e32 v4, 4, v3
	v_bitop3_b32 v3, v4, v3, 32 bitop3:0x6c
	v_ashrrev_i32_e32 v4, 31, v3
	v_lshrrev_b32_e32 v4, 26, v4
	v_add_u32_e32 v4, v3, v4
	v_lshlrev_b32_e32 v5, 3, v10
	v_ashrrev_i32_e32 v11, 6, v4
	v_and_b32_e32 v5, -16, v5
	v_add_u32_e32 v5, v11, v5
	v_and_b32_e32 v6, 3, v11
	s_mov_b32 s8, 0x1fffe0
	v_lshrrev_b32_e32 v7, 2, v5
	v_lshlrev_b32_e32 v8, 1, v5
	v_and_b32_e32 v4, 0xc0, v4
	v_and_or_b32 v6, v5, s8, v6
	v_and_b32_e32 v7, 4, v7
	v_and_b32_e32 v8, 24, v8
	v_sub_u32_e32 v3, v3, v4
	v_mov_b32_e32 v4, 1
	v_or3_b32 v6, v6, v7, v8
	v_lshlrev_b32_e32 v7, 5, v10
	v_ashrrev_i16_sdwa v3, v4, sext(v3) dst_sel:DWORD dst_unused:UNUSED_PAD src0_sel:DWORD src1_sel:BYTE_0
	v_and_b32_e32 v7, 32, v7
	v_bfe_i32 v12, v3, 0, 16
	v_add_lshl_u32 v3, v7, v12, 1
	v_lshl_add_u32 v174, v6, 11, v3
	v_lshl_add_u32 v176, v5, 11, v3
	v_bfe_i32 v3, v13, 27, 1
	v_lshrrev_b32_e32 v3, 22, v3
	v_add_u32_e32 v3, v2, v3
	s_mov_b64 s[6:7], s[26:27]
	v_and_b32_e32 v3, 0xfffffc00, v3
	v_sub_u32_e32 v2, v2, v3
	v_lshrrev_b32_e32 v3, 4, v2
	v_ashrrev_i32_e32 v5, 31, v13
	v_bitop3_b32 v2, v3, v2, 32 bitop3:0x6c
	v_lshrrev_b32_e32 v5, 26, v5
	v_ashrrev_i32_e32 v3, 31, v2
	v_add_u32_e32 v5, v13, v5
	s_waitcnt lgkmcnt(0)
	s_add_u32 s4, s6, 0x4b00000
	v_lshrrev_b32_e32 v3, 26, v3
	v_ashrrev_i32_e32 v15, 6, v5
	s_addc_u32 s5, s7, 0
	v_add_u32_e32 v3, v2, v3
	v_lshlrev_b32_e32 v5, 3, v15
	s_add_u32 s23, s6, 0x1a80000
	v_ashrrev_i32_e32 v14, 6, v3
	v_and_b32_e32 v5, -16, v5
	s_addc_u32 s24, s7, 0
	v_add_u32_e32 v5, v14, v5
	v_and_b32_e32 v6, 3, v14
	s_ashr_i32 s34, s2, 31
	v_and_or_b32 v6, v5, s8, v6
	s_lshr_b32 s8, s34, 29
	s_add_i32 s8, s2, s8
	s_ashr_i32 s41, s9, 6
	s_ashr_i32 s10, s8, 3
	s_and_b32 s8, s8, -8
	s_ashr_i32 s40, s9, 8
	s_lshl_b32 s25, s41, 10
	s_sub_i32 s8, s2, s8
	s_cmp_lt_i32 s8, 0
	s_movk_i32 s35, 0xb1
	s_cselect_b32 s11, s35, 0xb0
	s_mul_i32 s8, s11, s8
	s_add_i32 s8, s8, s10
	s_mul_hi_i32 s10, s8, 0x2e8ba2e9
	s_lshr_b32 s11, s10, 31
	s_ashr_i32 s10, s10, 5
	s_add_i32 s10, s10, s11
	s_lshl_b32 s11, s10, 3
	s_mulk_i32 s10, 0xb0
	s_sub_i32 s10, s8, s10
	s_sext_i32_i16 s8, s10
	s_bfe_u32 s8, s8, 0x3001c
	s_add_i32 s12, s10, s8
	s_sext_i32_i16 s8, s12
	s_and_b32 s12, s12, 0xfff8
	s_sub_i32 s10, s10, s12
	s_sext_i32_i16 s10, s10
	v_lshrrev_b32_e32 v7, 2, v5
	v_lshlrev_b32_e32 v8, 1, v5
	v_and_b32_e32 v3, 0xc0, v3
	s_lshr_b32 s8, s8, 3
	s_add_i32 s70, s11, s10
	v_and_b32_e32 v7, 4, v7
	v_and_b32_e32 v8, 24, v8
	v_sub_u32_e32 v2, v2, v3
	s_ashr_i32 s71, s70, 31
	s_bfe_i64 s[12:13], s[8:9], 0x100000
	v_or3_b32 v6, v6, v7, v8
	v_lshlrev_b32_e32 v7, 5, v15
	v_ashrrev_i16_sdwa v2, v4, sext(v2) dst_sel:DWORD dst_unused:UNUSED_PAD src0_sel:DWORD src1_sel:BYTE_0
	s_lshl_b64 s[10:11], s[70:71], 19
	s_lshl_b64 s[12:13], s[12:13], 19
	v_and_b32_e32 v7, 32, v7
	v_bfe_i32 v16, v2, 0, 16
	s_add_u32 s38, s23, s12
	v_add_lshl_u32 v2, v7, v16, 1
	s_addc_u32 s39, s24, s13
	s_add_i32 s36, s25, 0
	v_lshl_add_u32 v178, v6, 11, v2
	s_add_i32 m0, s36, 0x10000
	v_lshl_add_u32 v180, v5, 11, v2
	global_load_lds_dwordx4 v178, s[38:39]
	s_add_i32 m0, s36, 0x12000
	s_add_u32 s12, s38, 0x40000
	global_load_lds_dwordx4 v174, s[38:39]
	s_addc_u32 s13, s39, 0
	s_add_i32 m0, s36, 0x14000
	v_mov_b32_e32 v179, 0
	global_load_lds_dwordx4 v178, s[12:13]
	s_add_i32 m0, s36, 0x16000
	s_add_u32 s10, s4, s10
	s_addc_u32 s11, s5, s11
	s_add_i32 s37, s36, 0x2000
	global_load_lds_dwordx4 v174, s[12:13]
	s_mov_b32 m0, s36
	s_add_u32 s12, s10, 0x40000
	global_load_lds_dwordx4 v180, s[10:11]
	s_mov_b32 m0, s37
	s_addc_u32 s13, s11, 0
	s_add_i32 s42, s36, 0x4000
	global_load_lds_dwordx4 v176, s[10:11]
	s_mov_b32 m0, s42
	s_add_i32 s43, s36, 0x6000
	global_load_lds_dwordx4 v180, s[12:13]
	s_mov_b32 m0, s43
	v_mov_b32_e32 v175, v179
	global_load_lds_dwordx4 v176, s[12:13]
	v_readlane_b32 s12, v247, 36
	v_readlane_b32 s13, v247, 37
	v_readlane_b32 s14, v247, 38
	v_readlane_b32 s15, v247, 39
	s_nop 4
	v_mov_b32_e32 v181, v179
	v_mov_b32_e32 v177, v179
	s_cmp_eq_u32 s40, 1
	s_mov_b32 s44, 0
	v_lshl_add_u64 v[8:9], s[38:39], 0, v[178:179]
	v_lshl_add_u64 v[6:7], s[38:39], 0, v[174:175]
	v_lshl_add_u64 v[2:3], s[10:11], 0, v[180:181]
	s_cselect_b64 s[16:17], -1, 0
	s_cmp_lg_u32 s40, 1
	v_lshl_add_u64 v[4:5], s[10:11], 0, v[176:177]
	s_cbranch_scc1 .LBB0_828
	s_barrier

; __device__ __forceinline__ float sigm(float v) { return __builtin_amdgcn_rcpf(1.0f + __expf(-v)); }
;     __host__ __device__ void init(int M, int N, int G_, int c_) { base.init(M, N, G_, c_); G = G_; c = c_; }
;     __host__ __device__ void init(int M, int G_, int c_) { base.init(M, 1024, G_, c_); }
;     __host__ __device__ bool next(int i, Unit& u) const { Unit b; if (!base.next(i >> 1, b)) return false; u.pm = b.pm; u.pn = b.pn + 4 * (i & 1); return true; }
; __device__ __forceinline__ unsigned f2bf(float f) { unsigned u = __builtin_bit_cast(unsigned, f); return (u + 0x7fffu + ((u >> 16) & 1u)) >> 16; }
; __global__ void __launch_bounds__(512, 2) fwd_mega(Args a) {
;     ...
;         {
;             pg8::Gemm g{WSP(WS_ACT), WSP(l == 0 ? WS_WD : WS_WD1), M, D, FF, 1 << 20, 0}; pg8::StaticOrder S; S.init(M, D, G, bx);
;             {
;                 const float* cw = INF(18) + (size_t)l * 3 * FF; const float* cbp = INF(19) + (size_t)l * FF;
;                 const float* RA = (const float*)(a.ws + WS_RAWA); const float* RU = (const float*)(a.ws + WS_RAWU); const float* TA = (const float*)(a.ws + WS_TAILA);
;                 pg8::Unit fu;
;                 for (int i = 0; S.next(i, fu); ++i) {
;                     if ((fu.pm & 15) == 0) continue;
;                     for (int idx = threadIdx.x; idx < 2 * FF; idx += 512) {
;                         const int j = idx / FF, f = idx % FF; const size_t cur = (size_t)fu.pm * 2 * FF, prv = (size_t)(fu.pm - 1) * 2 * FF;
;                         const float a2 = RA[cur + j * FF + f], a1 = (j == 0) ? TA[prv + FF + f] : RA[cur + f], a0 = (j == 0) ? TA[prv + f] : TA[prv + FF + f];
;                         const float cv = cbp[f] + cw[f] * a0 + cw[FF + f] * a1 + cw[2 * FF + f] * a2;
;                         WSP(WS_ACT)[(size_t)(fu.pm * 256 + j) * FF + f] = (bf16)f2bf(cv * pg8::sigm(cv) * RU[cur + j * FF + f]);
;                     }
;                 }
;                 asm volatile("s_waitcnt vmcnt(0)" ::: "memory"); __syncthreads();
.LBB0_902:
	s_or_b64 exec, exec, s[6:7]
	s_waitcnt lgkmcnt(0)
	s_barrier
	s_mov_b64 s[12:13], s[26:27]
	v_readlane_b32 s8, v247, 36
	v_readlane_b32 s9, v247, 37
	v_readlane_b32 s10, v247, 38
	v_readlane_b32 s11, v247, 39
	s_nop 4
	s_mov_b32 s23, 0
	v_mov_b64_e32 v[2:3], 0x100
	v_mov_b64_e32 v[4:5], 0xff
	s_waitcnt lgkmcnt(0)
	s_add_u32 s20, s12, 0x6b00000
	s_addc_u32 s21, s13, 0
	s_add_u32 s14, s12, 0x200000
	s_addc_u32 s15, s13, 0
	s_add_u32 s16, s12, 0x380000
	s_addc_u32 s17, s13, 0
	s_add_u32 s4, s12, 0x500000
	s_addc_u32 s5, s13, 0
	s_ashr_i32 s67, s3, 31
	s_ashr_i32 s65, s2, 31
	s_movk_i32 s24, 0x1600
	s_movk_i32 s25, 0xaff
	v_mov_b32_e32 v7, 0
	s_movk_i32 s30, 0x2000
	s_movk_i32 s31, 0x5000
	s_movk_i32 s34, 0x7fff
	s_movk_i32 s35, 0x13ff
	v_mov_b32_e32 v10, 0xb00
	v_mov_b64_e32 v[8:9], s[20:21]
	s_branch .LBB0_905

; #define PG8_STAGE(bufoff, gbase, voff) do { _Pragma("unroll") for (int _i = 0; _i < 2; ++_i) \
;         __builtin_amdgcn_global_load_lds((const unsigned*)((const char*)(gbase) + (voff)[_i]), (PG8_LAS unsigned*)(lds + (bufoff) + ldsw + _i * 8192), 16, 0, 0); } while (0)
; #define PG8_WAIT_V(n) asm volatile("s_waitcnt vmcnt(" #n ")" ::: "memory")
; #define PG8_BAR __builtin_amdgcn_s_barrier()
; template <class Epi, class Sched, bool ALIGN_EPI = false, bool SP2 = false, bool PAIR_ACC = false>
; __device__ __forceinline__ void gemm_phase(PG8_LAS unsigned char* lds, const Gemm g, const Sched& S, const Epi& E) {
;     ...
;     for (int i = 0; i < 2; ++i) { int R, C; stage_rc(tid * 16 + i * 8192, R, C); const int Rb = Epi::PERM ? ((R & ~31) + perm32(R & 31)) : R;
;         voffA[i] = (unsigned)(R * K + C) * 2u; voffB[i] = (unsigned)(Rb * K + C) * 2u; }
;     const size_t kstep = (size_t)(BK * 2);
;     const size_t hstep = (size_t)HALF * K * 2;
;     const size_t tstep = 2 * hstep;
;     const unsigned ldsw = (unsigned)wid * 1024u;
;     const int aoff = lds_byte(wr * 64 + fr, fq * 8), boff = lds_byte(wc * 32 + fr, fq * 8);
;     ...
;     Unit cur, nxt; int ui = 0;
;     if (!S.next(0, cur)) return;
;     f32x4 acc[2][2][4][2];
; #pragma unroll
;     for (int a = 0; a < 2; ++a)
; #pragma unroll
;         for (int b = 0; b < 2; ++b)
; #pragma unroll
;             for (int m = 0; m < 4; ++m)
; #pragma unroll
;                 for (int n = 0; n < 2; ++n) acc[a][b][m][n] = (f32x4){0.f, 0.f, 0.f, 0.f};
;     bf16x8 At[4][2], B0[2][2], B1[2][2];
;     const char* cA = (const char*)g.A + (size_t)cur.pm * tstep + (size_t)(cur.pn / g.a_div) * g.a_sel; const char* cB = (const char*)g.Bt + (size_t)cur.pn * tstep;
;     S.a_ready(cur);
;     if constexpr (SP2) {
;         PG8_STAGE(PG8_SB(0, 0), cB, voffB); PG8_STAGE(PG8_SB(0, 1), cB + hstep, voffB); PG8_STAGE(PG8_SA(0, 0), cA, voffA); PG8_STAGE(PG8_SA(0, 1), cA + hstep, voffA);
;         if (wr == 1) PG8_BAR;
;         PG8_WAIT_V(2); PG8_BAR;
;         PG8_STAGE(PG8_SB(1, 0), cB + kstep, voffB); PG8_STAGE(PG8_SA(1, 0), cA + kstep, voffA); PG8_STAGE(PG8_SB(1, 1), cB + hstep + kstep, voffB);
;         PG8_WAIT_V(6); PG8_BAR;
; __global__ void __launch_bounds__(512, 2) fwd_mega(Args a) {
;     ...
;                 pg8::EpiResidNorm<false, true> E{WSP(WS_XMID), (void*)a.out, ml + 5120, WSP(WS_H), INF(5) + (l + 1) * D, ml + 4 * 6144, 0, 1024, st};
.LBB0_921:
	v_ashrrev_i32_e32 v3, 31, v168
	v_lshrrev_b32_e32 v3, 26, v3
	v_add_u32_e32 v3, v168, v3
	v_ashrrev_i32_e32 v10, 6, v3
	v_bfe_i32 v3, v168, 27, 1
	v_lshlrev_b32_e32 v2, 4, v168
	v_lshrrev_b32_e32 v3, 22, v3
	v_add_u32_e32 v3, v2, v3
	v_and_b32_e32 v3, 0xfffffc00, v3
	v_sub_u32_e32 v3, v2, v3
	v_lshrrev_b32_e32 v4, 4, v3
	v_bitop3_b32 v3, v4, v3, 32 bitop3:0x6c
	v_ashrrev_i32_e32 v5, 31, v3
	v_lshrrev_b32_e32 v5, 26, v5
	v_lshlrev_b32_e32 v4, 3, v10
	v_add_u32_e32 v5, v3, v5
	v_and_b32_e32 v4, -16, v4
	v_ashrrev_i32_e32 v12, 6, v5
	v_and_b32_e32 v5, 0xc0, v5
	v_add_u32_e32 v4, v12, v4
	v_lshlrev_b32_e32 v6, 5, v10
	v_sub_u32_e32 v3, v3, v5
	v_mov_b32_e32 v5, 1
	s_ashr_i32 s7, s8, 3
	v_and_b32_e32 v11, 32, v6
	v_ashrrev_i16_sdwa v3, v5, sext(v3) dst_sel:DWORD dst_unused:UNUSED_PAD src0_sel:DWORD src1_sel:BYTE_0
	v_lshlrev_b32_e32 v6, 1, v4
	v_lshrrev_b32_e32 v7, 2, v4
	v_and_b32_e32 v8, 3, v12
	s_mov_b32 s8, 0xffffe0
	v_bfe_i32 v13, v3, 0, 16
	v_and_b32_e32 v6, 24, v6
	v_and_b32_e32 v7, 4, v7
	v_and_or_b32 v8, v4, s8, v8
	s_movk_i32 s6, 0xb00
	v_add_u32_e32 v3, v11, v13
	v_or3_b32 v6, v8, v7, v6
	v_mul_lo_u32 v4, v4, s6
	v_add_lshl_u32 v130, v3, v4, 1
	v_mul_u32_u24_e32 v4, 0xb00, v6
	v_add_u32_e32 v2, 0x2000, v2
	v_add_lshl_u32 v132, v4, v3, 1
	v_ashrrev_i32_e32 v3, 31, v2
	v_lshrrev_b32_e32 v3, 22, v3
	v_add_u32_e32 v3, v2, v3
	v_ashrrev_i32_e32 v14, 10, v3
	v_mul_i32_i24_e32 v3, 0x400, v14
	v_sub_u32_e32 v2, v2, v3
	v_lshrrev_b32_e32 v3, 4, v2
	v_bitop3_b32 v2, v3, v2, 32 bitop3:0x6c
	s_add_u32 s34, s12, 0x2580000
	v_ashrrev_i32_e32 v4, 31, v2
	s_addc_u32 s35, s13, 0
	v_lshrrev_b32_e32 v4, 26, v4
	s_add_i32 s5, s5, s7
	v_lshlrev_b32_e32 v3, 3, v14
	v_add_u32_e32 v4, v2, v4
	s_ashr_i32 s7, s5, 31
	v_and_b32_e32 v3, -16, v3
	v_ashrrev_i32_e32 v15, 6, v4
	v_lshlrev_b32_e32 v6, 5, v14
	s_lshr_b32 s7, s7, 27
	v_add_u32_e32 v3, v15, v3
	v_and_b32_e32 v16, 32, v6
	v_and_b32_e32 v6, 3, v15
	s_add_i32 s7, s5, s7
	v_and_or_b32 v6, v3, s8, v6
	s_ashr_i32 s8, s7, 5
	s_andn2_b32 s7, s7, 31
	s_sub_i32 s5, s5, s7
	s_bfe_i32 s7, s5, 0x80000
	s_bfe_u32 s7, s7, 0x3000c
	s_add_i32 s9, s5, s7
	s_bfe_i32 s7, s9, 0x80000
	s_and_b32 s9, s9, 0xf8
	s_sub_i32 s5, s5, s9
	s_lshl_b32 s8, s8, 3
	s_sext_i32_i16 s10, s7
	s_sext_i32_i8 s5, s5
	s_ashr_i32 s19, s4, 6
	v_and_b32_e32 v4, 0xc0, v4
	s_add_i32 s5, s8, s5
	s_ashr_i32 s8, s10, 3
	s_ashr_i32 s24, s4, 8
	v_sub_u32_e32 v2, v2, v4
	s_lshl_b32 s36, s19, 10
	s_lshr_b32 s7, s10, 3
	s_mul_hi_i32 s9, s8, 0x160000
	s_mul_i32 s8, s8, 0x160000
	v_ashrrev_i16_sdwa v2, v5, sext(v2) dst_sel:DWORD dst_unused:UNUSED_PAD src0_sel:DWORD src1_sel:BYTE_0
	v_lshlrev_b32_e32 v4, 1, v3
	v_lshrrev_b32_e32 v5, 2, v3
	s_add_u32 s50, s34, s8
	v_bfe_i32 v17, v2, 0, 16
	v_and_b32_e32 v4, 24, v4
	v_and_b32_e32 v5, 4, v5
	s_addc_u32 s51, s35, s9
	s_add_i32 s37, s36, 0
	v_add_u32_e32 v2, v16, v17
	v_or3_b32 v4, v6, v5, v4
	v_mul_lo_u32 v3, v3, s6
	s_add_i32 m0, s37, 0x10000
	v_add_lshl_u32 v134, v2, v3, 1
	v_mul_u32_u24_e32 v3, 0xb00, v4
	global_load_lds_dwordx4 v132, s[50:51]
	s_add_i32 m0, s37, 0x12000
	v_add_lshl_u32 v136, v3, v2, 1
	s_add_u32 s8, s50, 0xb0000
	global_load_lds_dwordx4 v136, s[50:51]
	s_addc_u32 s9, s51, 0
	s_add_i32 m0, s37, 0x14000
	s_mul_i32 s14, s5, 0x160000
	global_load_lds_dwordx4 v132, s[8:9]
	s_add_i32 m0, s37, 0x16000
	s_mul_hi_i32 s11, s5, 0x160000
	s_add_u32 s28, s20, s14
	s_addc_u32 s29, s21, s11
	s_add_i32 s40, s37, 0x2000
	global_load_lds_dwordx4 v136, s[8:9]
	s_mov_b32 m0, s37
	s_add_u32 s8, s28, 0xb0000
	global_load_lds_dwordx4 v130, s[28:29]
	s_mov_b32 m0, s40
	s_addc_u32 s9, s29, 0
	s_add_i32 s41, s37, 0x4000
	global_load_lds_dwordx4 v134, s[28:29]
	s_mov_b32 m0, s41
	s_add_i32 s42, s37, 0x6000
	global_load_lds_dwordx4 v130, s[8:9]
	s_mov_b32 m0, s42
	v_mov_b32_e32 v133, 0
	global_load_lds_dwordx4 v134, s[8:9]
	v_readlane_b32 s14, v247, 10
	v_readlane_b32 s15, v247, 11
	v_readlane_b32 s16, v247, 44
	v_readlane_b32 s17, v247, 45
	s_nop 4
	v_mov_b32_e32 v137, v133
	v_mov_b32_e32 v131, v133
	v_mov_b32_e32 v135, v133
	s_mov_b32 s43, 0
	v_lshl_add_u64 v[8:9], s[50:51], 0, v[132:133]
	v_lshl_add_u64 v[6:7], s[50:51], 0, v[136:137]
	v_lshl_add_u64 v[4:5], s[28:29], 0, v[130:131]
	s_cmp_lg_u32 s24, 1
	v_lshl_add_u64 v[2:3], s[28:29], 0, v[134:135]
	s_cbranch_scc1 .LBB0_923
	s_barrier

; #define LAS __attribute__((address_space(3)))
; __global__ void __launch_bounds__(512, 2) fwd_mega(Args a) {
;     ...
;     auto convert_items = [&](int LL, int lo, int hi, int w0, int nw_, size_t wd_off) __attribute__((always_inline)) {
;         LAS float* scr = (LAS float*)(lds + wave * 16384);
;         for (int it0 = lo + w0; it0 < hi; it0 += nw_) {
;             int it = it0;
;             if (it < 2688) { const int kb = it / 168, nb = it % 168; tr_item(INF(6) + (size_t)LL * D * INC, INC, WSP(WS_WIN), 1024, 0, 32 * nb, 64 * kb, 32 * nb, scr, lane); continue; } it -= 2688;
;             if (it < 512) { const int kb = it / 32, nb = it % 32; tr_item(INF(13) + (size_t)LL * D * D, D, WSP(WS_PAB), 1024, 0, 32 * nb, 64 * kb, 32 * nb, scr, lane); continue; } it -= 512;
;             if (it < 512) { const int kb = it / 32, nb = it % 32; tr_item(INF(12) + (size_t)LL * D * D, D, WSP(WS_PAB), 1024, 0, 1024 + 32 * nb, 64 * kb, 32 * nb, scr, lane); continue; } it -= 512;
;             if (it < 512) { const int kb = it / 32, nb = it % 32; tr_item(INF(14) + (size_t)LL * D * D, D, WSP(WS_WO2), 1024, 0, 32 * nb, 64 * kb, 32 * nb, scr, lane); continue; } it -= 512;
;             if (it < 1408) { const int kb = it / 88, nb = it % 88, n0 = 32 * nb; tr_item(INF(16) + (size_t)LL * D * FF, FF, WSP(WS_WGU), 1024, 0, (n0 >> 7) * 256 + (n0 & 127), 64 * kb, n0, scr, lane); continue; } it -= 1408;
;             if (it < 1408) { const int kb = it / 88, nb = it % 88, n0 = 32 * nb; tr_item(INF(17) + (size_t)LL * D * FF, FF, WSP(WS_WGU), 1024, 0, (n0 >> 7) * 256 + 128 + (n0 & 127), 64 * kb, n0, scr, lane); continue; } it -= 1408;
;             { const int kb = it / 32, nb = it % 32; tr_item(INF(20) + (size_t)LL * FF * D, D, WSP(wd_off), 2816, 0, 32 * nb, 64 * kb, 32 * nb, scr, lane); }
;         }
;     };
;     ...
;             convert_items(l + 1, 0, 8448, gw, NGW, WS_WD1);
.LBB0_983:
	v_readlane_b32 s4, v246, 4
	v_readlane_b32 s5, v246, 5
	s_andn2_b64 vcc, exec, s[4:5]
	s_barrier
	s_cbranch_vccnz .LBB0_1010
	v_readlane_b32 s4, v247, 40
	v_readlane_b32 s5, v247, 41
	s_nop 4
	s_mov_b64 s[6:7], s[26:27]
	v_lshlrev_b32_e32 v2, 2, v205
	v_mul_u32_u24_e32 v6, 0x84, v200
	v_readlane_b32 s10, v246, 3
	v_mov_b32_e32 v3, 0
	v_mov_b32_e32 v7, v3
	v_add3_u32 v28, s10, v2, v6
	v_and_b32_e32 v6, 56, v204
	v_mul_u32_u24_e32 v8, 0x84, v6
	v_lshlrev_b32_e32 v6, 1, v6
	s_waitcnt lgkmcnt(0)
	v_lshl_add_u64 v[4:5], s[4:5], 0, v[2:3]
	v_lshl_add_u64 v[26:27], s[6:7], 0, v[6:7]
	s_mov_b64 s[4:5], 0xf600000
	v_lshl_add_u64 v[6:7], v[26:27], 0, s[4:5]
	v_readlane_b32 s4, v247, 32
	v_readlane_b32 s5, v247, 33
	v_readlane_b32 s6, v247, 34
	v_readlane_b32 s7, v247, 35
	s_nop 4
	v_lshlrev_b32_e32 v9, 2, v201
	s_mov_b64 s[8:9], 0xb00000
	v_add3_u32 v29, s10, v8, v9
	v_readlane_b32 s10, v247, 28
	v_readlane_b32 s11, v247, 29
	s_nop 4
	s_waitcnt lgkmcnt(0)
	v_lshl_add_u64 v[8:9], s[6:7], 0, v[2:3]
	s_mov_b64 s[6:7], 0x1a80000
	v_lshl_add_u64 v[12:13], s[4:5], 0, v[2:3]
	v_lshl_add_u64 v[4:5], v[4:5], 0, s[8:9]
	v_lshl_add_u64 v[8:9], v[8:9], 0, s[8:9]
	v_lshl_add_u64 v[10:11], v[26:27], 0, s[6:7]
	v_lshl_add_u64 v[12:13], v[12:13], 0, s[8:9]
	v_readlane_b32 s8, v247, 12
	v_readlane_b32 s9, v247, 13
	v_readlane_b32 s4, v247, 24
	v_readlane_b32 s5, v247, 25
	v_readlane_b32 s6, v247, 26
	v_readlane_b32 s7, v247, 27
	s_nop 4
	v_lshl_add_u64 v[14:15], s[10:11], 0, v[2:3]
	s_mov_b64 s[10:11], 0x400000
	s_mov_b64 s[12:13], 0x1680000
	s_waitcnt vmcnt(3) lgkmcnt(0)
	v_lshl_add_u64 v[24:25], s[8:9], 0, v[2:3]
	s_waitcnt vmcnt(1)
	v_lshl_add_u64 v[18:19], s[4:5], 0, v[2:3]
	s_mov_b64 s[4:5], 0x1280000
	v_lshl_add_u64 v[20:21], v[26:27], 0, s[4:5]
	s_mov_b64 s[4:5], 0x1500000
	v_lshl_add_u64 v[22:23], s[6:7], 0, v[2:3]
	v_lshl_add_u64 v[24:25], v[24:25], 0, s[4:5]
	s_mov_b64 s[4:5], 0x800000
	v_or_b32_e32 v30, 8, v201
	v_or_b32_e32 v31, 16, v201
	v_or_b32_e32 v32, 24, v201
	v_lshl_add_u64 v[14:15], v[14:15], 0, s[10:11]
	v_lshl_add_u64 v[16:17], v[26:27], 0, s[12:13]
	v_lshl_add_u64 v[18:19], v[18:19], 0, s[10:11]
	v_lshl_add_u64 v[22:23], v[22:23], 0, s[10:11]
	v_lshl_add_u64 v[26:27], v[26:27], 0, s[4:5]
	s_lshl_b32 s4, s22, 5
	s_lshl_b32 s5, s77, 5
	s_lshl_b32 s12, s22, 1
	s_lshl_b32 s13, s77, 1
	s_mov_b32 s7, 0
	s_movk_i32 s14, 0x7fff
	s_mov_b32 s15, 0xffff0000
	s_movk_i32 s16, 0x5000
	s_mov_b32 s17, 0xb000
	s_mov_b32 s18, 0x10000
	s_mov_b32 s19, 0x16000
	s_mov_b32 s20, 0x1b000
	s_mov_b32 s21, 0x21000
	s_mov_b32 s23, 0x26000
	s_mov_b32 s24, 0x2c000
	s_mov_b32 s25, 0x31000
	s_mov_b32 s28, 0x37000
	s_mov_b32 s29, 0x3c000
	s_mov_b32 s30, 0x42000
	s_mov_b32 s31, 0x47000
	s_mov_b32 s34, 0x4d000
	s_mov_b32 s35, 0x52000
	s_mov_b32 s36, 0x58000
	s_mov_b32 s37, 0x5d000
	s_mov_b32 s38, 0x63000
	s_mov_b32 s39, 0x68000
	s_mov_b32 s40, 0x6e000
	s_mov_b32 s41, 0x73000
	s_mov_b32 s42, 0x79000
	s_mov_b32 s43, 0x7e000
	s_mov_b32 s44, 0x84000
	s_mov_b32 s45, 0x89000
	s_mov_b32 s46, 0x8f000
	s_mov_b32 s47, 0x94000
	s_mov_b32 s48, 0x9a000
	s_mov_b32 s49, 0x9f000
	s_mov_b32 s50, 0xa5000
	s_mov_b32 s51, 0xaa000
	s_movk_i32 s52, 0x5400
	v_add_u32_e32 v33, 0x400, v28
	v_add_u32_e32 v34, 0x800, v28
	v_add_u32_e32 v35, 0xc00, v28
	v_add_u32_e32 v36, 0x1000, v28
	v_add_u32_e32 v37, 0x1400, v28
	v_add_u32_e32 v38, 0x1800, v28
	v_add_u32_e32 v39, 0x1c00, v28
	s_mov_b32 s53, s22
	s_branch .LBB0_986

; __device__ __forceinline__ unsigned cvt_pk_bf16(float lo, float hi) { unsigned r; asm volatile("v_cvt_pk_bf16_f32 %0, %1, %2" : "=v"(r) : "v"(lo), "v"(hi)); return r; }
; __device__ __forceinline__ void sgu_wfrag_item(const float* Wl, v4u* WF, int item, int lane) {
;     const int g = item / 20, q = item % 20, fr = lane & 15, fq = lane >> 4;
;     int mt = 0, ks = 0, c = 0;
;     for (int m = 0; m < 8; ++m) for (int k = 0; k <= (m >> 1); ++k) { if (c == q) { mt = m; ks = k; } ++c; }
;     const int t = 16 * mt + fr, sb = 32 * ks + 8 * fq;
;     const float* p = Wl + ((size_t)g * 128 + t) * 128 + sb;
;     const f32x4 wa = *(const f32x4*)p, wb = *(const f32x4*)(p + 4);
;     v4u ww;
;     ww.x = cvt_pk_bf16(sb + 0 <= t ? wa.x : 0.f, sb + 1 <= t ? wa.y : 0.f); ww.y = cvt_pk_bf16(sb + 2 <= t ? wa.z : 0.f, sb + 3 <= t ? wa.w : 0.f);
;     ww.z = cvt_pk_bf16(sb + 4 <= t ? wb.x : 0.f, sb + 5 <= t ? wb.y : 0.f); ww.w = cvt_pk_bf16(sb + 6 <= t ? wb.z : 0.f, sb + 7 <= t ? wb.w : 0.f);
;     WF[(size_t)item * 64 + lane] = ww;
; __global__ void __launch_bounds__(512, 2) fwd_mega(Args a) {
;     ...
;             for (int it = gw; it < 160; it += NGW) sgu_wfrag_item(INF(10) + (size_t)(l + 1) * 8 * 128 * 128, (v4u*)(a.ws + WS_WF), it, lane);
.LBB0_1010:
	v_readlane_b32 s4, v246, 6
	v_readlane_b32 s5, v246, 7
	s_andn2_b64 vcc, exec, s[4:5]
	s_cbranch_vccnz .LBB0_1013
	v_readlane_b32 s4, v247, 20
	v_readlane_b32 s5, v247, 21
	s_nop 4
	s_mov_b64 s[6:7], s[26:27]
	v_mov_b32_e32 v173, 0
	v_and_b32_e32 v4, 24, v203
	s_waitcnt lgkmcnt(0)
	s_add_u32 s4, s4, 0x80000
	v_lshl_add_u64 v[2:3], s[6:7], 0, v[172:173]
	s_mov_b64 s[6:7], 0x680000
	s_addc_u32 s5, s5, 0
	v_lshl_add_u64 v[2:3], v[2:3], 0, s[6:7]

; __device__ __forceinline__ void attn_unit(LAS unsigned char* lds, bf16* Q, const bf16* Kg, const bf16* Vg, const float* snk, int unit, int tid) {
;     const int lane = tid & 63, wave = tid >> 6, fr = lane & 15, fq = lane >> 4;
;     const int b = unit >> 6, n = (unit >> 1) & 31, h = unit & 1, r0 = b * SEQ + n * 128, hq = 8 * h + wave;
;     const v4u zero4 = {0u, 0u, 0u, 0u};
;     bf16* qbase = Q + (size_t)(r0 + fr) * 1024 + hq * 64;
;     bf16x8_t qf[8][2];
; #pragma unroll
;     for (int mt = 0; mt < 8; ++mt) { qf[mt][0] = *(const bf16x8_t*)(qbase + (size_t)mt * 16 * 1024 + 8 * fq); qf[mt][1] = *(const bf16x8_t*)(qbase + (size_t)mt * 16 * 1024 + 32 + 8 * fq); }
; #pragma unroll
;     for (int i = 0; i < 4; ++i) { const int idx = tid + 512 * i, j = idx >> 3, c = idx & 7, p = n * 128 - 128 + j;
;         v4u w = zero4; if (p >= 0) w = *(const v4u*)(Kg + (size_t)(b * SEQ + p) * 128 + h * 64 + c * 8);
;         *(LAS v4u*)(lds + j * ATT_KP + c * 16) = w; }
; #pragma unroll
;     for (int i = 0; i < 2; ++i) { const int idx = tid + 512 * i, j = (idx >> 3) * 2, c = idx & 7, p = n * 128 - 128 + j;
;         v4u w0 = zero4, w1 = zero4;
;         if (p >= 0) { w0 = *(const v4u*)(Vg + (size_t)(b * SEQ + p) * 128 + h * 64 + c * 8); w1 = *(const v4u*)(Vg + (size_t)(b * SEQ + p + 1) * 128 + h * 64 + c * 8); }
;         const unsigned A0[4] = {w0.x, w0.y, w0.z, w0.w}, A1[4] = {w1.x, w1.y, w1.z, w1.w};
; #pragma unroll
;         for (int e = 0; e < 8; ++e) { const unsigned lo = (e & 1) ? (A0[e >> 1] >> 16) : (A0[e >> 1] & 0xffffu), hi = (e & 1) ? (A1[e >> 1] & 0xffff0000u) : (A1[e >> 1] << 16);
;             *(LAS unsigned*)(lds + ATT_VOFF + (8 * c + e) * ATT_VP + j * 2) = lo | hi; } }
;     __syncthreads();
;     const float sink = snk[hq] * 1.4426950408889634f;
;     bool lo_ok[4];
; #pragma unroll
;     for (int i = 0; i < 4; ++i) lo_ok[i] = (4 * fq + i - fr) > 0;
; __global__ void __launch_bounds__(512, 2) fwd_mega(Args a) {
;     ...
;         {
;             int tid_ = threadIdx.x; asm volatile("" : "+v"(tid_));
;             for (int it = bx; it < 512; it += G) {
;                 if (it < 256) attn_unit(lds, WSP(WS_Q), WSP(WS_K), WSP(WS_V), INF(7) + l * 16, it, tid_);
;                 else sgu_unit(lds, WSP(WS_U), WSP(WS_VS), (const float*)(a.ws + WS_SGS), INF(8) + l * 1024, INF(9) + l * 1024, (const v4u*)(a.ws + WS_WF), INF(11) + l * 8 * 128, it - 256, tid_);
.LBB0_1394:
	s_or_b64 exec, exec, s[6:7]
	v_readlane_b32 s4, v246, 18
	v_readlane_b32 s5, v246, 19
	v_mov_b32_e32 v161, v0
	s_andn2_b64 vcc, exec, s[4:5]
	s_waitcnt lgkmcnt(0)
	s_barrier
	s_cbranch_vccnz .LBB0_1415
	s_movk_i32 s4, 0x80
	v_cmp_gt_i32_e64 s[6:7], s4, v161
	v_ashrrev_i32_e32 v169, 6, v161
	s_movk_i32 s4, 0x4400
	v_mul_lo_u32 v5, v169, s4
	s_mov_b64 s[4:5], s[26:27]
	v_readlane_b32 s28, v247, 14
	v_readlane_b32 s29, v247, 15
	v_readlane_b32 s30, v247, 16
	v_readlane_b32 s31, v247, 17
	v_readlane_b32 s16, v247, 18
	v_readlane_b32 s17, v247, 19
	v_readlane_b32 s18, v247, 22
	v_readlane_b32 s19, v247, 23
	s_nop 4
	v_and_b32_e32 v6, 7, v161
	v_add_u32_e32 v8, 0x200, v161
	v_lshlrev_b32_e32 v170, 3, v6
	s_waitcnt lgkmcnt(0)
	s_add_u32 s38, s4, 0x4b00000
	s_addc_u32 s39, s5, 0
	s_add_u32 s30, s30, 0x1000
	s_addc_u32 s31, s31, 0
	s_add_u32 s40, s16, 0x1000
	v_mul_u32_u24_e32 v10, 0x110, v6
	v_bfe_u32 v15, v161, 4, 2
	v_lshlrev_b32_e32 v4, 4, v6
	s_waitcnt vmcnt(1)
	v_mul_u32_u24_e32 v20, 0x1080, v6
	v_ashrrev_i32_e32 v6, 2, v8
	s_addc_u32 s41, s17, 0
	v_add_u32_e32 v9, 0x400, v161
	v_and_b32_e32 v176, -2, v6
	v_lshlrev_b32_e32 v6, 2, v15
	s_add_u32 s44, s18, 0x1000
	v_and_b32_e32 v3, 63, v161
	v_and_b32_e32 v163, 15, v161
	v_ashrrev_i32_e32 v172, 3, v8
	v_ashrrev_i32_e32 v173, 3, v9
	v_add_u32_e32 v9, 0x600, v161
	v_or_b32_e32 v8, 2, v6
	s_addc_u32 s45, s19, 0
	v_mov_b32_e32 v147, 0
	v_ashrrev_i32_e32 v174, 3, v9
	v_ashrrev_i32_e32 v9, 2, v161
	v_cmp_gt_u32_e64 s[12:13], v8, v163
	v_or_b32_e32 v8, 3, v6
	v_lshlrev_b32_e32 v146, 4, v3
	s_add_u32 s46, s4, 0xf400000
	v_add_u32_e32 v3, 0, v5
	v_lshrrev_b32_e32 v5, 1, v161
	v_bfe_u32 v2, v161, 3, 3
	v_and_b32_e32 v175, -2, v9
	v_cmp_gt_u32_e64 s[14:15], v8, v163
	v_lshl_add_u64 v[8:9], s[4:5], 0, v[146:147]
	s_mov_b64 s[16:17], 0x680000
	s_addc_u32 s47, s5, 0
	v_and_b32_e32 v146, 24, v5
	v_lshlrev_b32_e32 v167, 3, v161
	v_lshlrev_b32_e32 v7, 11, v2
	v_lshlrev_b32_e32 v11, 2, v2
	v_lshlrev_b32_e32 v12, 4, v2
	v_bfe_u32 v2, v161, 3, 1
	v_lshl_add_u64 v[148:149], v[8:9], 0, s[16:17]
	v_lshl_add_u64 v[8:9], s[4:5], 0, v[146:147]
	s_mov_b64 s[16:17], 0x9300000
	s_add_u32 s50, s4, 0x6b00000
	v_mov_b32_e32 v5, v147
	v_and_or_b32 v2, v167, 56, v2
	v_lshl_add_u64 v[150:151], v[8:9], 0, s[16:17]
	s_addc_u32 s51, s5, 0
	v_add_u32_e32 v8, 0, v4
	v_lshl_add_u64 v[4:5], s[4:5], 0, v[4:5]
	s_mov_b64 s[4:5], 0x8b00000
	v_mul_u32_u24_e32 v14, 0x110, v2
	v_lshlrev_b32_e32 v2, 3, v15
	v_lshl_add_u64 v[152:153], v[4:5], 0, s[4:5]
	s_mov_b64 s[4:5], 0x8f00000
	v_lshl_add_u32 v9, v15, 4, 0
	v_and_b32_e32 v13, 48, v161
	v_ashrrev_i32_e32 v171, 3, v161
	s_movk_i32 s20, 0x90
	v_add3_u32 v177, v3, v10, v11
	v_lshl_add_u64 v[154:155], v[4:5], 0, s[4:5]
	v_sub_u32_e32 v10, v9, v2
	s_movk_i32 s4, 0x210
	v_mul_lo_u32 v16, v171, s20
	v_mul_lo_u32 v17, v172, s20
	v_mul_lo_u32 v18, v173, s20
	v_mul_lo_u32 v19, v174, s20
	v_add_u32_e32 v3, v3, v13
	v_lshl_add_u32 v4, v175, 1, 0
	v_lshl_add_u32 v5, v176, 1, 0
	v_mad_u32_u24 v179, v163, s4, v10
	s_lshl_b32 s4, s2, 2
	v_ashrrev_i32_e32 v165, 7, v161
	v_and_b32_e32 v168, 64, v161
	v_cmp_gt_u32_e64 s[8:9], v6, v163
	v_cmp_lt_u32_e64 s[10:11], v6, v163
	s_mov_b32 s49, 0
	v_mad_u32_u24 v178, v163, s20, v9
	s_addk_i32 s4, 0xfc00
	s_lshl_b32 s5, s3, 2
	s_lshl_b32 s24, s2, 6
	s_lshl_b32 s25, s3, 6
	s_movk_i32 s34, 0x1000
	s_movk_i32 s35, 0x2000
	s_movk_i32 s36, 0x3000
	s_movk_i32 s37, 0x4000
	s_mov_b32 s52, 0x3a800000
	s_mov_b32 s42, 0x800000
	v_lshlrev_b32_e32 v180, 1, v7
	s_mov_b32 s43, 0x8000
	s_mov_b32 s53, 0x10000
	s_mov_b32 s54, 0x18000
	s_mov_b32 s55, 0x20000
	s_mov_b32 s56, 0x28000
	s_mov_b32 s57, 0x30000
	s_mov_b32 s58, 0x38000
	v_add_u32_e32 v181, 0, v12
	s_mov_b32 s59, 0xffff0000
	v_add_u32_e32 v182, v3, v14
	v_lshlrev_b32_e32 v146, 1, v2
	v_add_u32_e32 v183, v8, v16
	v_add_u32_e32 v184, v8, v17
	v_add_u32_e32 v185, v8, v18
	v_add_u32_e32 v186, v8, v19
	s_mov_b32 s60, 0xffff
	v_add_u32_e32 v187, v4, v20
	v_add_u32_e32 v188, v5, v20
	s_mov_b32 s61, 0x3fb8aa3b
	v_lshlrev_b32_e32 v156, 1, v6
	v_mbcnt_hi_u32_b32 v189, -1, v1
	v_mov_b32_e32 v190, 0xff800000
	s_mov_b32 s62, s2
	s_branch .LBB0_1398

;     __host__ __device__ void init(int M, int N, int G_, int c_) { base.init(M, N, G_, c_); G = G_; c = c_; }
;     __host__ __device__ void init(int M, int G_, int c_) { base.init(M, 1024, G_, c_); }
;     __host__ __device__ bool next(int i, Unit& u) const { Unit b; if (!base.next(i >> 1, b)) return false; u.pm = b.pm; u.pn = b.pn + 4 * (i & 1); return true; }
;     __host__ __device__ bool next(int i, Unit& u) const {
;         const long L = (long)i * G + c; if (L >= nwg) return false;
;         int wgid = (int)L; { const int q = nwg / NXCD, r = nwg % NXCD, xcd = wgid % NXCD, off = wgid / NXCD; wgid = (xcd < r ? xcd * (q + 1) : r * (q + 1) + (xcd - r) * q) + off; }
;         const int nig = WGM * nN, gid = wgid / nig, fm = gid * WGM, gsz = (nM - fm) < WGM ? (nM - fm) : WGM;
;         u.pm = fm + ((wgid % nig) % gsz); u.pn = (wgid % nig) / gsz; return true;
; __global__ void __launch_bounds__(512, 2) fwd_mega(Args a) {
;     ...
;             pg8::Gemm g{WSP(WS_MG), WSP(WS_WO2), M, D, D, 1 << 20, 0}; pg8::StaticOrder S; S.init(M, D, G, bx);
;             const float* ml = (const float*)(a.ws + WS_MOD) + (size_t)l * 4 * 6144;
;     ...
;             if constexpr (l == 0) {
;                 pg8::EpiResidNorm<false, false> E{INF(0), WSP(WS_XMID), ml + 2048, WSP(WS_H2), INF(15) + l * D, ml, 3072, 4096, st};
;                 pg8::gemm_phase<pg8::EpiResidNorm<false, false>, pg8::StaticOrder, false, true>(lds, g, S, E);
;             } else {
;                 pg8::EpiResidNorm<false, true> E{(const void*)a.out, WSP(WS_XMID), ml + 2048, WSP(WS_H2), INF(15) + l * D, ml, 3072, 4096, st};
;                 pg8::gemm_phase<pg8::EpiResidNorm<false, true>, pg8::StaticOrder, false, true>(lds, g, S, E);
.LBB0_1613:
	s_or_b64 exec, exec, s[6:7]
	v_mov_b32_e32 v168, v0
	s_waitcnt lgkmcnt(0)
	s_barrier
	s_and_b64 vcc, exec, s[74:75]
	v_readfirstlane_b32 s4, v168
	s_cbranch_vccnz .LBB0_1676
	s_lshr_b32 s5, s65, 29
	s_add_i32 s8, s2, s5
	s_and_b32 s5, s8, -8
	s_sub_i32 s9, s2, s5
	s_cmp_gt_i32 s9, -1
	s_cbranch_scc0 .LBB0_1616
	s_lshl_b32 s5, s9, 5
	v_readlane_b32 s12, v247, 44
	v_readlane_b32 s13, v247, 45
	v_readlane_b32 s14, v247, 46
	v_readlane_b32 s15, v247, 47
	s_nop 4
	s_cbranch_execz .LBB0_1617
	s_branch .LBB0_1618
.LBB0_1616:
	v_readlane_b32 s12, v247, 44
	v_readlane_b32 s13, v247, 45
	v_readlane_b32 s14, v247, 46
	v_readlane_b32 s15, v247, 47
	s_nop 4

; #define PG8_STAGE(bufoff, gbase, voff) do { _Pragma("unroll") for (int _i = 0; _i < 2; ++_i) \
;         __builtin_amdgcn_global_load_lds((const unsigned*)((const char*)(gbase) + (voff)[_i]), (PG8_LAS unsigned*)(lds + (bufoff) + ldsw + _i * 8192), 16, 0, 0); } while (0)
; #define PG8_WAIT_V(n) asm volatile("s_waitcnt vmcnt(" #n ")" ::: "memory")
; #define PG8_BAR __builtin_amdgcn_s_barrier()
; template <class Epi, class Sched, bool ALIGN_EPI = false, bool SP2 = false, bool PAIR_ACC = false>
; __device__ __forceinline__ void gemm_phase(PG8_LAS unsigned char* lds, const Gemm g, const Sched& S, const Epi& E) {
;     ...
;     for (int i = 0; i < 2; ++i) { int R, C; stage_rc(tid * 16 + i * 8192, R, C); const int Rb = Epi::PERM ? ((R & ~31) + perm32(R & 31)) : R;
;         voffA[i] = (unsigned)(R * K + C) * 2u; voffB[i] = (unsigned)(Rb * K + C) * 2u; }
;     const size_t kstep = (size_t)(BK * 2);
;     const size_t hstep = (size_t)HALF * K * 2;
;     const size_t tstep = 2 * hstep;
;     const unsigned ldsw = (unsigned)wid * 1024u;
;     const int aoff = lds_byte(wr * 64 + fr, fq * 8), boff = lds_byte(wc * 32 + fr, fq * 8);
;     ...
;     Unit cur, nxt; int ui = 0;
;     if (!S.next(0, cur)) return;
;     f32x4 acc[2][2][4][2];
; #pragma unroll
;     for (int a = 0; a < 2; ++a)
; #pragma unroll
;         for (int b = 0; b < 2; ++b)
; #pragma unroll
;             for (int m = 0; m < 4; ++m)
; #pragma unroll
;                 for (int n = 0; n < 2; ++n) acc[a][b][m][n] = (f32x4){0.f, 0.f, 0.f, 0.f};
;     bf16x8 At[4][2], B0[2][2], B1[2][2];
;     const char* cA = (const char*)g.A + (size_t)cur.pm * tstep + (size_t)(cur.pn / g.a_div) * g.a_sel; const char* cB = (const char*)g.Bt + (size_t)cur.pn * tstep;
;     S.a_ready(cur);
;     if constexpr (SP2) {
;         PG8_STAGE(PG8_SB(0, 0), cB, voffB); PG8_STAGE(PG8_SB(0, 1), cB + hstep, voffB); PG8_STAGE(PG8_SA(0, 0), cA, voffA); PG8_STAGE(PG8_SA(0, 1), cA + hstep, voffA);
;         if (wr == 1) PG8_BAR;
;         PG8_WAIT_V(2); PG8_BAR;
;         PG8_STAGE(PG8_SB(1, 0), cB + kstep, voffB); PG8_STAGE(PG8_SA(1, 0), cA + kstep, voffA); PG8_STAGE(PG8_SB(1, 1), cB + hstep + kstep, voffB);
;         PG8_WAIT_V(6); PG8_BAR;
; __global__ void __launch_bounds__(512, 2) fwd_mega(Args a) {
;     ...
;                 pg8::EpiResidNorm<false, true> E{(const void*)a.out, WSP(WS_XMID), ml + 2048, WSP(WS_H2), INF(15) + l * D, ml, 3072, 4096, st};
.LBB0_1618:
	v_ashrrev_i32_e32 v3, 31, v168
	v_lshrrev_b32_e32 v3, 26, v3
	v_add_u32_e32 v3, v168, v3
	v_ashrrev_i32_e32 v10, 6, v3
	v_bfe_i32 v3, v168, 27, 1
	v_lshlrev_b32_e32 v2, 4, v168
	v_lshrrev_b32_e32 v3, 22, v3
	v_add_u32_e32 v3, v2, v3
	v_and_b32_e32 v3, 0xfffffc00, v3
	v_sub_u32_e32 v3, v2, v3
	v_lshrrev_b32_e32 v4, 4, v3
	v_bitop3_b32 v3, v4, v3, 32 bitop3:0x6c
	v_ashrrev_i32_e32 v5, 31, v3
	v_lshrrev_b32_e32 v5, 26, v5
	v_add_u32_e32 v5, v3, v5
	v_lshlrev_b32_e32 v4, 3, v10
	v_ashrrev_i32_e32 v11, 6, v5
	v_and_b32_e32 v5, 0xc0, v5
	v_and_b32_e32 v4, -16, v4
	v_sub_u32_e32 v3, v3, v5
	v_mov_b32_e32 v5, 1
	v_add_u32_e32 v4, v11, v4
	v_ashrrev_i16_sdwa v3, v5, sext(v3) dst_sel:DWORD dst_unused:UNUSED_PAD src0_sel:DWORD src1_sel:BYTE_0
	v_lshlrev_b32_e32 v6, 5, v10
	v_bfe_i32 v12, v3, 0, 16
	v_lshlrev_b32_e32 v3, 1, v4
	v_lshrrev_b32_e32 v7, 2, v4
	v_and_b32_e32 v8, 3, v11
	s_mov_b32 s7, 0x1fffe0
	v_and_b32_e32 v6, 32, v6
	v_and_b32_e32 v3, 24, v3
	v_and_b32_e32 v7, 4, v7
	v_and_or_b32 v8, v4, s7, v8
	v_or3_b32 v3, v8, v7, v3
	v_add_lshl_u32 v6, v6, v12, 1
	v_add_u32_e32 v2, 0x2000, v2
	v_lshl_add_u32 v132, v3, 11, v6
	v_ashrrev_i32_e32 v3, 31, v2
	v_lshrrev_b32_e32 v3, 22, v3
	v_add_u32_e32 v3, v2, v3
	v_ashrrev_i32_e32 v13, 10, v3
	v_mul_i32_i24_e32 v3, 0x400, v13
	v_sub_u32_e32 v2, v2, v3
	s_ashr_i32 s6, s8, 3
	v_lshrrev_b32_e32 v3, 4, v2
	s_waitcnt lgkmcnt(0)
	s_add_u32 s25, s14, 0x2b00000
	v_bitop3_b32 v2, v3, v2, 32 bitop3:0x6c
	s_addc_u32 s34, s15, 0
	v_lshl_add_u32 v130, v4, 11, v6
	v_ashrrev_i32_e32 v4, 31, v2
	s_add_u32 s35, s14, 0x1680000
	v_lshrrev_b32_e32 v4, 26, v4
	s_addc_u32 s36, s15, 0
	v_add_u32_e32 v4, v2, v4
	s_add_i32 s5, s5, s6
	v_lshlrev_b32_e32 v3, 3, v13
	v_ashrrev_i32_e32 v14, 6, v4
	v_and_b32_e32 v4, 0xc0, v4
	s_ashr_i32 s6, s5, 31
	v_and_b32_e32 v3, -16, v3
	v_sub_u32_e32 v2, v2, v4
	s_lshr_b32 s6, s6, 27
	v_add_u32_e32 v3, v14, v3
	v_ashrrev_i16_sdwa v2, v5, sext(v2) dst_sel:DWORD dst_unused:UNUSED_PAD src0_sel:DWORD src1_sel:BYTE_0
	v_and_b32_e32 v5, 3, v14
	s_add_i32 s6, s5, s6
	v_and_or_b32 v5, v3, s7, v5
	s_ashr_i32 s7, s6, 5
	s_andn2_b32 s6, s6, 31
	s_sub_i32 s5, s5, s6
	s_bfe_i32 s6, s5, 0x80000
	s_bfe_u32 s6, s6, 0x3000c
	s_add_i32 s8, s5, s6
	s_bfe_i32 s6, s8, 0x80000
	s_and_b32 s8, s8, 0xf8
	s_sub_i32 s5, s5, s8
	s_lshl_b32 s7, s7, 3
	s_sext_i32_i16 s6, s6
	s_sext_i32_i8 s5, s5
	s_lshr_b32 s6, s6, 3
	s_add_i32 s18, s7, s5
	s_ashr_i32 s11, s4, 6
	s_ashr_i32 s19, s18, 31
	s_bfe_i64 s[16:17], s[6:7], 0x100000
	s_ashr_i32 s24, s4, 8
	s_lshl_b32 s37, s11, 10
	s_lshl_b64 s[8:9], s[18:19], 19
	s_lshl_b64 s[16:17], s[16:17], 19
	s_add_u32 s44, s35, s16
	v_lshlrev_b32_e32 v6, 5, v13
	v_bfe_i32 v15, v2, 0, 16
	v_lshlrev_b32_e32 v2, 1, v3
	v_lshrrev_b32_e32 v4, 2, v3
	s_addc_u32 s45, s36, s17
	s_add_i32 s50, s37, 0
	v_and_b32_e32 v6, 32, v6
	v_and_b32_e32 v2, 24, v2
	v_and_b32_e32 v4, 4, v4
	s_add_i32 m0, s50, 0x10000
	v_or3_b32 v2, v5, v4, v2
	v_add_lshl_u32 v4, v6, v15, 1
	global_load_lds_dwordx4 v132, s[44:45]
	s_add_i32 m0, s50, 0x12000
	v_lshl_add_u32 v136, v2, 11, v4
	s_add_u32 s16, s44, 0x40000
	global_load_lds_dwordx4 v136, s[44:45]
	s_addc_u32 s17, s45, 0
	s_add_i32 m0, s50, 0x14000
	v_lshl_add_u32 v134, v3, 11, v4
	global_load_lds_dwordx4 v132, s[16:17]
	s_add_i32 m0, s50, 0x16000
	s_add_u32 s20, s25, s8
	s_addc_u32 s21, s34, s9
	s_add_i32 s51, s50, 0x2000
	global_load_lds_dwordx4 v136, s[16:17]
	s_mov_b32 m0, s50
	s_add_u32 s8, s20, 0x40000
	global_load_lds_dwordx4 v130, s[20:21]
	s_mov_b32 m0, s51
	s_addc_u32 s9, s21, 0
	s_add_i32 s52, s50, 0x4000
	global_load_lds_dwordx4 v134, s[20:21]
	s_mov_b32 m0, s52
	s_add_i32 s53, s50, 0x6000
	global_load_lds_dwordx4 v130, s[8:9]
	s_mov_b32 m0, s53
	v_readlane_b32 s16, v247, 30
	v_readlane_b32 s17, v247, 31
	s_nop 4
	global_load_lds_dwordx4 v134, s[8:9]
	v_mov_b32_e32 v133, 0
	v_mov_b32_e32 v137, v133
	v_mov_b32_e32 v131, v133
	v_mov_b32_e32 v135, v133
	s_mov_b32 s54, 0
	v_lshl_add_u64 v[8:9], s[44:45], 0, v[132:133]
	v_lshl_add_u64 v[6:7], s[44:45], 0, v[136:137]
	v_lshl_add_u64 v[4:5], s[20:21], 0, v[130:131]
	s_cmp_lg_u32 s24, 1
	v_lshl_add_u64 v[2:3], s[20:21], 0, v[134:135]
	s_cbranch_scc1 .LBB0_1620
	s_barrier

; #define PG8_WAIT_V(n) asm volatile("s_waitcnt vmcnt(" #n ")" ::: "memory")
;     __host__ __device__ bool next(int i, Unit& u) const {
;         const long L = (long)i * G + c; if (L >= nwg) return false;
;         int wgid = (int)L; { const int q = nwg / NXCD, r = nwg % NXCD, xcd = wgid % NXCD, off = wgid / NXCD; wgid = (xcd < r ? xcd * (q + 1) : r * (q + 1) + (xcd - r) * q) + off; }
;         const int nig = WGM * nN, gid = wgid / nig, fm = gid * WGM, gsz = (nM - fm) < WGM ? (nM - fm) : WGM;
;         u.pm = fm + ((wgid % nig) % gsz); u.pn = (wgid % nig) / gsz; return true;
; template <class Epi, class Sched, bool ALIGN_EPI = false, bool SP2 = false, bool PAIR_ACC = false>
; __device__ __forceinline__ void gemm_phase(PG8_LAS unsigned char* lds, const Gemm g, const Sched& S, const Epi& E) {
;     ...
;     for (int i = 0; i < 2; ++i) { int R, C; stage_rc(tid * 16 + i * 8192, R, C); const int Rb = Epi::PERM ? ((R & ~31) + perm32(R & 31)) : R;
;         voffA[i] = (unsigned)(R * K + C) * 2u; voffB[i] = (unsigned)(Rb * K + C) * 2u; }
;     const size_t kstep = (size_t)(BK * 2);
;     const size_t hstep = (size_t)HALF * K * 2;
;     const size_t tstep = 2 * hstep;
;     const unsigned ldsw = (unsigned)wid * 1024u;
;     const int aoff = lds_byte(wr * 64 + fr, fq * 8), boff = lds_byte(wc * 32 + fr, fq * 8);
;     ...
;     Unit cur, nxt; int ui = 0;
;     if (!S.next(0, cur)) return;
;     f32x4 acc[2][2][4][2];
; #pragma unroll
;     for (int a = 0; a < 2; ++a)
; #pragma unroll
;         for (int b = 0; b < 2; ++b)
; #pragma unroll
;             for (int m = 0; m < 4; ++m)
; #pragma unroll
;                 for (int n = 0; n < 2; ++n) acc[a][b][m][n] = (f32x4){0.f, 0.f, 0.f, 0.f};
;     bf16x8 At[4][2], B0[2][2], B1[2][2];
;     const char* cA = (const char*)g.A + (size_t)cur.pm * tstep + (size_t)(cur.pn / g.a_div) * g.a_sel; const char* cB = (const char*)g.Bt + (size_t)cur.pn * tstep;
;     S.a_ready(cur);
;     if constexpr (SP2) {
;         PG8_STAGE(PG8_SB(0, 0), cB, voffB); PG8_STAGE(PG8_SB(0, 1), cB + hstep, voffB); PG8_STAGE(PG8_SA(0, 0), cA, voffA); PG8_STAGE(PG8_SA(0, 1), cA + hstep, voffA);
;         if (wr == 1) PG8_BAR;
;         PG8_WAIT_V(2); PG8_BAR;
;         PG8_STAGE(PG8_SB(1, 0), cB + kstep, voffB); PG8_STAGE(PG8_SA(1, 0), cA + kstep, voffA); PG8_STAGE(PG8_SB(1, 1), cB + hstep + kstep, voffB);
;         PG8_WAIT_V(6); PG8_BAR;
.LBB0_1728:
	s_or_b64 exec, exec, s[6:7]
	v_readlane_b32 s4, v246, 16
	v_mov_b32_e32 v12, v0
	v_readlane_b32 s5, v246, 17
	s_waitcnt lgkmcnt(0)
	s_barrier
	s_andn2_b64 vcc, exec, s[4:5]
	v_readfirstlane_b32 s42, v12
	s_cbranch_vccnz .LBB0_1753
	v_lshlrev_b32_e32 v2, 4, v12
	v_add_u32_e32 v3, 0x2000, v2
	v_ashrrev_i32_e32 v4, 31, v3
	v_lshrrev_b32_e32 v4, 22, v4
	v_add_u32_e32 v4, v3, v4
	v_ashrrev_i32_e32 v10, 10, v4
	v_mul_i32_i24_e32 v4, 0x400, v10
	v_sub_u32_e32 v3, v3, v4
	v_lshrrev_b32_e32 v4, 4, v3
	v_bitop3_b32 v3, v4, v3, 32 bitop3:0x6c
	v_ashrrev_i32_e32 v4, 31, v3
	v_lshrrev_b32_e32 v4, 26, v4
	v_add_u32_e32 v4, v3, v4
	v_lshlrev_b32_e32 v5, 3, v10
	v_ashrrev_i32_e32 v11, 6, v4
	v_and_b32_e32 v5, -16, v5
	v_add_u32_e32 v5, v11, v5
	v_and_b32_e32 v6, 3, v11
	s_mov_b32 s8, 0x1fffe0
	v_lshrrev_b32_e32 v7, 2, v5
	v_lshlrev_b32_e32 v8, 1, v5
	v_and_b32_e32 v4, 0xc0, v4
	v_and_or_b32 v6, v5, s8, v6
	v_and_b32_e32 v7, 4, v7
	v_and_b32_e32 v8, 24, v8
	v_sub_u32_e32 v3, v3, v4
	v_mov_b32_e32 v4, 1
	v_or3_b32 v6, v6, v7, v8
	v_lshlrev_b32_e32 v7, 5, v10
	v_ashrrev_i16_sdwa v3, v4, sext(v3) dst_sel:DWORD dst_unused:UNUSED_PAD src0_sel:DWORD src1_sel:BYTE_0
	v_and_b32_e32 v7, 32, v7
	v_bfe_i32 v13, v3, 0, 16
	v_add_lshl_u32 v3, v7, v13, 1
	v_lshl_add_u32 v172, v6, 11, v3
	v_lshl_add_u32 v174, v5, 11, v3
	v_bfe_i32 v3, v12, 27, 1
	v_lshrrev_b32_e32 v3, 22, v3
	v_add_u32_e32 v3, v2, v3
	v_and_b32_e32 v3, 0xfffffc00, v3
	s_mov_b64 s[6:7], s[26:27]
	v_sub_u32_e32 v2, v2, v3
	v_lshrrev_b32_e32 v3, 4, v2
	v_ashrrev_i32_e32 v5, 31, v12
	v_bitop3_b32 v2, v3, v2, 32 bitop3:0x6c
	v_lshrrev_b32_e32 v5, 26, v5
	v_ashrrev_i32_e32 v3, 31, v2
	v_add_u32_e32 v5, v12, v5
	v_lshrrev_b32_e32 v3, 26, v3
	v_ashrrev_i32_e32 v15, 6, v5
	s_waitcnt lgkmcnt(0)
	s_add_u32 s4, s6, 0x4b00000
	v_add_u32_e32 v3, v2, v3
	v_lshlrev_b32_e32 v5, 3, v15
	s_addc_u32 s5, s7, 0
	v_ashrrev_i32_e32 v14, 6, v3
	v_and_b32_e32 v5, -16, v5
	s_add_u32 s24, s6, 0x1a80000
	v_add_u32_e32 v5, v14, v5
	v_and_b32_e32 v6, 3, v14
	s_addc_u32 s25, s7, 0
	v_and_or_b32 v6, v5, s8, v6
	s_lshr_b32 s8, s65, 29
	s_add_i32 s8, s2, s8
	s_ashr_i32 s30, s42, 6
	s_ashr_i32 s9, s8, 3
	s_and_b32 s8, s8, -8
	s_ashr_i32 s44, s42, 8
	s_lshl_b32 s34, s30, 10
	s_sub_i32 s8, s2, s8
	s_cmp_lt_i32 s8, 0
	s_movk_i32 s35, 0xb1
	s_cselect_b32 s10, s35, 0xb0
	s_mul_i32 s8, s10, s8
	s_add_i32 s8, s8, s9
	s_mul_hi_i32 s9, s8, 0x2e8ba2e9
	s_lshr_b32 s10, s9, 31
	s_ashr_i32 s9, s9, 5
	s_add_i32 s9, s9, s10
	s_lshl_b32 s10, s9, 3
	s_mulk_i32 s9, 0xb0
	s_sub_i32 s8, s8, s9
	s_sext_i32_i16 s9, s8
	s_bfe_u32 s9, s9, 0x3001c
	s_add_i32 s9, s8, s9
	s_sext_i32_i16 s11, s9
	s_and_b32 s9, s9, 0xfff8
	s_sub_i32 s8, s8, s9
	s_sext_i32_i16 s8, s8
	v_lshrrev_b32_e32 v7, 2, v5
	v_lshlrev_b32_e32 v8, 1, v5
	v_and_b32_e32 v3, 0xc0, v3
	s_lshr_b32 s38, s11, 3
	s_add_i32 s58, s10, s8
	v_and_b32_e32 v7, 4, v7
	v_and_b32_e32 v8, 24, v8
	v_sub_u32_e32 v2, v2, v3
	s_ashr_i32 s59, s58, 31
	s_bfe_i64 s[10:11], s[38:39], 0x100000
	v_or3_b32 v6, v6, v7, v8
	v_lshlrev_b32_e32 v7, 5, v15
	v_ashrrev_i16_sdwa v2, v4, sext(v2) dst_sel:DWORD dst_unused:UNUSED_PAD src0_sel:DWORD src1_sel:BYTE_0
	s_lshl_b64 s[8:9], s[58:59], 19
	s_lshl_b64 s[10:11], s[10:11], 19
	v_and_b32_e32 v7, 32, v7
	v_bfe_i32 v16, v2, 0, 16
	s_add_u32 s60, s24, s10
	v_add_lshl_u32 v2, v7, v16, 1
	s_addc_u32 s61, s25, s11
	s_add_i32 s36, s34, 0
	v_lshl_add_u32 v176, v6, 11, v2
	s_add_i32 m0, s36, 0x10000
	v_lshl_add_u32 v178, v5, 11, v2
	global_load_lds_dwordx4 v176, s[60:61]
	s_add_i32 m0, s36, 0x12000
	s_add_u32 s10, s60, 0x40000
	global_load_lds_dwordx4 v172, s[60:61]
	s_addc_u32 s11, s61, 0
	s_add_i32 m0, s36, 0x14000
	v_mov_b32_e32 v177, 0
	global_load_lds_dwordx4 v176, s[10:11]
	s_add_i32 m0, s36, 0x16000
	s_add_u32 s62, s4, s8
	s_addc_u32 s63, s5, s9
	s_add_i32 s37, s36, 0x2000
	global_load_lds_dwordx4 v172, s[10:11]
	s_mov_b32 m0, s36
	s_add_u32 s8, s62, 0x40000
	global_load_lds_dwordx4 v178, s[62:63]
	s_mov_b32 m0, s37
	s_addc_u32 s9, s63, 0
	s_add_i32 s49, s36, 0x4000
	global_load_lds_dwordx4 v174, s[62:63]
	s_mov_b32 m0, s49
	s_add_i32 s64, s36, 0x6000
	global_load_lds_dwordx4 v178, s[8:9]
	s_mov_b32 m0, s64
	v_mov_b32_e32 v173, v177
	global_load_lds_dwordx4 v174, s[8:9]
	v_readlane_b32 s8, v247, 36
	v_readlane_b32 s9, v247, 37
	v_readlane_b32 s10, v247, 38
	v_readlane_b32 s11, v247, 39
	s_nop 4
	v_mov_b32_e32 v179, v177
	v_mov_b32_e32 v175, v177
	s_cmp_eq_u32 s44, 1
	s_mov_b32 s66, 0
	v_lshl_add_u64 v[8:9], s[60:61], 0, v[176:177]
	v_lshl_add_u64 v[6:7], s[60:61], 0, v[172:173]
	v_lshl_add_u64 v[2:3], s[62:63], 0, v[178:179]
	s_cselect_b64 s[12:13], -1, 0
	s_cmp_lg_u32 s44, 1
	v_lshl_add_u64 v[4:5], s[62:63], 0, v[174:175]
	s_cbranch_scc1 .LBB0_1731
	s_barrier

; __device__ __forceinline__ float sigm(float v) { return __builtin_amdgcn_rcpf(1.0f + __expf(-v)); }
;     __host__ __device__ void init(int M, int N, int G_, int c_) { base.init(M, N, G_, c_); G = G_; c = c_; }
;     __host__ __device__ void init(int M, int G_, int c_) { base.init(M, 1024, G_, c_); }
;     __host__ __device__ bool next(int i, Unit& u) const { Unit b; if (!base.next(i >> 1, b)) return false; u.pm = b.pm; u.pn = b.pn + 4 * (i & 1); return true; }
; __device__ __forceinline__ unsigned f2bf(float f) { unsigned u = __builtin_bit_cast(unsigned, f); return (u + 0x7fffu + ((u >> 16) & 1u)) >> 16; }
; __global__ void __launch_bounds__(512, 2) fwd_mega(Args a) {
;     ...
;             pg8::Gemm g{WSP(WS_ACT), WSP(l == 0 ? WS_WD : WS_WD1), M, D, FF, 1 << 20, 0}; pg8::StaticOrder S; S.init(M, D, G, bx);
;             {
;                 const float* cw = INF(18) + (size_t)l * 3 * FF; const float* cbp = INF(19) + (size_t)l * FF;
;                 const float* RA = (const float*)(a.ws + WS_RAWA); const float* RU = (const float*)(a.ws + WS_RAWU); const float* TA = (const float*)(a.ws + WS_TAILA);
;                 pg8::Unit fu;
;                 for (int i = 0; S.next(i, fu); ++i) {
;                     if ((fu.pm & 15) == 0) continue;
;                     for (int idx = threadIdx.x; idx < 2 * FF; idx += 512) {
;                         const int j = idx / FF, f = idx % FF; const size_t cur = (size_t)fu.pm * 2 * FF, prv = (size_t)(fu.pm - 1) * 2 * FF;
;                         const float a2 = RA[cur + j * FF + f], a1 = (j == 0) ? TA[prv + FF + f] : RA[cur + f], a0 = (j == 0) ? TA[prv + f] : TA[prv + FF + f];
;                         const float cv = cbp[f] + cw[f] * a0 + cw[FF + f] * a1 + cw[2 * FF + f] * a2;
;                         WSP(WS_ACT)[(size_t)(fu.pm * 256 + j) * FF + f] = (bf16)f2bf(cv * pg8::sigm(cv) * RU[cur + j * FF + f]);
;                     }
;                 }
;                 asm volatile("s_waitcnt vmcnt(0)" ::: "memory"); __syncthreads();
.LBB0_1805:
	s_or_b64 exec, exec, s[6:7]
	s_waitcnt lgkmcnt(0)
	s_barrier
	v_readlane_b32 s4, v247, 36
	v_readlane_b32 s5, v247, 37
	v_readlane_b32 s6, v247, 38
	v_readlane_b32 s7, v247, 39
	v_readlane_b32 s12, v247, 46
	v_readlane_b32 s13, v247, 47
	s_nop 4
	s_mov_b32 s24, 0
	v_mov_b64_e32 v[2:3], 0x100
	v_mov_b64_e32 v[4:5], 0xff
	s_waitcnt lgkmcnt(0)
	s_add_u32 s8, s4, 0x8400
	s_addc_u32 s9, s5, 0
	s_add_u32 s10, s6, 0x2c00
	s_addc_u32 s11, s7, 0
	s_add_u32 s14, s12, 0x200000
	s_addc_u32 s15, s13, 0
	s_add_u32 s18, s12, 0x380000
	s_addc_u32 s19, s13, 0
	s_add_u32 s4, s12, 0x500000
	s_addc_u32 s5, s13, 0
	s_add_u32 s16, s12, 0x6b00000
	s_addc_u32 s17, s13, 0
	s_movk_i32 s25, 0x1600
	s_movk_i32 s26, 0xaff
	v_mov_b32_e32 v7, 0
	s_movk_i32 s27, 0x2000
	s_movk_i32 s28, 0x5000
	s_movk_i32 s29, 0x7fff
	s_movk_i32 s30, 0x13ff
	v_mov_b32_e32 v10, 0xb00
	v_mov_b64_e32 v[8:9], s[16:17]
	s_branch .LBB0_1808

; #define PG8_STAGE(bufoff, gbase, voff) do { _Pragma("unroll") for (int _i = 0; _i < 2; ++_i) \
;         __builtin_amdgcn_global_load_lds((const unsigned*)((const char*)(gbase) + (voff)[_i]), (PG8_LAS unsigned*)(lds + (bufoff) + ldsw + _i * 8192), 16, 0, 0); } while (0)
; #define PG8_WAIT_V(n) asm volatile("s_waitcnt vmcnt(" #n ")" ::: "memory")
; #define PG8_BAR __builtin_amdgcn_s_barrier()
; template <class Epi, class Sched, bool ALIGN_EPI = false, bool SP2 = false, bool PAIR_ACC = false>
; __device__ __forceinline__ void gemm_phase(PG8_LAS unsigned char* lds, const Gemm g, const Sched& S, const Epi& E) {
;     ...
;     for (int i = 0; i < 2; ++i) { int R, C; stage_rc(tid * 16 + i * 8192, R, C); const int Rb = Epi::PERM ? ((R & ~31) + perm32(R & 31)) : R;
;         voffA[i] = (unsigned)(R * K + C) * 2u; voffB[i] = (unsigned)(Rb * K + C) * 2u; }
;     const size_t kstep = (size_t)(BK * 2);
;     const size_t hstep = (size_t)HALF * K * 2;
;     const size_t tstep = 2 * hstep;
;     const unsigned ldsw = (unsigned)wid * 1024u;
;     const int aoff = lds_byte(wr * 64 + fr, fq * 8), boff = lds_byte(wc * 32 + fr, fq * 8);
;     ...
;     Unit cur, nxt; int ui = 0;
;     if (!S.next(0, cur)) return;
;     f32x4 acc[2][2][4][2];
; #pragma unroll
;     for (int a = 0; a < 2; ++a)
; #pragma unroll
;         for (int b = 0; b < 2; ++b)
; #pragma unroll
;             for (int m = 0; m < 4; ++m)
; #pragma unroll
;                 for (int n = 0; n < 2; ++n) acc[a][b][m][n] = (f32x4){0.f, 0.f, 0.f, 0.f};
;     bf16x8 At[4][2], B0[2][2], B1[2][2];
;     const char* cA = (const char*)g.A + (size_t)cur.pm * tstep + (size_t)(cur.pn / g.a_div) * g.a_sel; const char* cB = (const char*)g.Bt + (size_t)cur.pn * tstep;
;     S.a_ready(cur);
;     if constexpr (SP2) {
;         PG8_STAGE(PG8_SB(0, 0), cB, voffB); PG8_STAGE(PG8_SB(0, 1), cB + hstep, voffB); PG8_STAGE(PG8_SA(0, 0), cA, voffA); PG8_STAGE(PG8_SA(0, 1), cA + hstep, voffA);
;         if (wr == 1) PG8_BAR;
;         PG8_WAIT_V(2); PG8_BAR;
;         PG8_STAGE(PG8_SB(1, 0), cB + kstep, voffB); PG8_STAGE(PG8_SA(1, 0), cA + kstep, voffA); PG8_STAGE(PG8_SB(1, 1), cB + hstep + kstep, voffB);
;         PG8_WAIT_V(6); PG8_BAR;
; __global__ void __launch_bounds__(512, 2) fwd_mega(Args a) {
;     ...
;                 pg8::EpiResidNorm<true, true> E{WSP(WS_XMID), (void*)a.out, ml + 5120, nullptr, INF(21), ml, 0, 0, st};
.LBB0_1824:
	v_ashrrev_i32_e32 v3, 31, v0
	v_lshrrev_b32_e32 v3, 26, v3
	v_add_u32_e32 v3, v0, v3
	v_ashrrev_i32_e32 v10, 6, v3
	v_bfe_i32 v3, v0, 27, 1
	v_lshlrev_b32_e32 v2, 4, v0
	v_lshrrev_b32_e32 v3, 22, v3
	v_add_u32_e32 v3, v2, v3
	v_and_b32_e32 v3, 0xfffffc00, v3
	v_sub_u32_e32 v3, v2, v3
	v_lshrrev_b32_e32 v4, 4, v3
	v_bitop3_b32 v3, v4, v3, 32 bitop3:0x6c
	v_ashrrev_i32_e32 v5, 31, v3
	v_lshrrev_b32_e32 v5, 26, v5
	v_lshlrev_b32_e32 v4, 3, v10
	v_add_u32_e32 v5, v3, v5
	v_and_b32_e32 v4, -16, v4
	v_ashrrev_i32_e32 v12, 6, v5
	v_and_b32_e32 v5, 0xc0, v5
	v_add_u32_e32 v4, v12, v4
	v_lshlrev_b32_e32 v6, 5, v10
	v_sub_u32_e32 v3, v3, v5
	v_mov_b32_e32 v5, 1
	v_and_b32_e32 v11, 32, v6
	v_ashrrev_i16_sdwa v3, v5, sext(v3) dst_sel:DWORD dst_unused:UNUSED_PAD src0_sel:DWORD src1_sel:BYTE_0
	v_lshlrev_b32_e32 v6, 1, v4
	v_lshrrev_b32_e32 v7, 2, v4
	v_and_b32_e32 v8, 3, v12
	s_mov_b32 s7, 0xffffe0
	v_bfe_i32 v13, v3, 0, 16
	v_and_b32_e32 v6, 24, v6
	v_and_b32_e32 v7, 4, v7
	v_and_or_b32 v8, v4, s7, v8
	s_movk_i32 s4, 0xb00
	v_add_u32_e32 v3, v11, v13
	v_or3_b32 v6, v8, v7, v6
	v_mul_lo_u32 v4, v4, s4
	v_add_lshl_u32 v130, v3, v4, 1
	v_mul_u32_u24_e32 v4, 0xb00, v6
	v_add_u32_e32 v2, 0x2000, v2
	v_add_lshl_u32 v132, v4, v3, 1
	v_ashrrev_i32_e32 v3, 31, v2
	v_lshrrev_b32_e32 v3, 22, v3
	v_add_u32_e32 v3, v2, v3
	v_ashrrev_i32_e32 v14, 10, v3
	v_mul_i32_i24_e32 v3, 0x400, v14
	v_sub_u32_e32 v2, v2, v3
	v_lshrrev_b32_e32 v3, 4, v2
	v_bitop3_b32 v2, v3, v2, 32 bitop3:0x6c
	s_add_u32 s35, s12, 0xf600000
	v_ashrrev_i32_e32 v4, 31, v2
	s_addc_u32 s36, s13, 0
	v_lshrrev_b32_e32 v4, 26, v4
	s_add_i32 s5, s6, s5
	v_lshlrev_b32_e32 v3, 3, v14
	v_add_u32_e32 v4, v2, v4
	s_ashr_i32 s6, s5, 31
	v_and_b32_e32 v3, -16, v3
	v_ashrrev_i32_e32 v15, 6, v4
	v_lshlrev_b32_e32 v6, 5, v14
	s_lshr_b32 s6, s6, 27
	v_add_u32_e32 v3, v15, v3
	v_and_b32_e32 v16, 32, v6
	v_and_b32_e32 v6, 3, v15
	s_add_i32 s6, s5, s6
	v_and_or_b32 v6, v3, s7, v6
	s_ashr_i32 s7, s6, 5
	s_and_b32 s6, s6, 0xffe0
	s_sub_i32 s6, s5, s6
	s_bfe_i32 s5, s6, 0x80000
	s_bfe_u32 s5, s5, 0x3000c
	s_add_i32 s8, s6, s5
	s_bfe_i32 s5, s8, 0x80000
	s_and_b32 s8, s8, 0xf8
	s_sub_i32 s6, s6, s8
	s_lshl_b32 s7, s7, 3
	s_sext_i32_i16 s9, s5
	s_sext_i32_i8 s6, s6
	s_ashr_i32 s15, s30, 6
	v_and_b32_e32 v4, 0xc0, v4
	s_add_i32 s31, s7, s6
	s_ashr_i32 s6, s9, 3
	v_sub_u32_e32 v2, v2, v4
	s_ashr_i32 s33, s30, 8
	s_lshl_b32 s37, s15, 10
	s_lshr_b32 s5, s9, 3
	s_mul_hi_i32 s7, s6, 0x160000
	s_mul_i32 s6, s6, 0x160000
	v_ashrrev_i16_sdwa v2, v5, sext(v2) dst_sel:DWORD dst_unused:UNUSED_PAD src0_sel:DWORD src1_sel:BYTE_0
	v_lshlrev_b32_e32 v4, 1, v3
	v_lshrrev_b32_e32 v5, 2, v3
	s_add_u32 s24, s35, s6
	v_bfe_i32 v17, v2, 0, 16
	v_and_b32_e32 v4, 24, v4
	v_and_b32_e32 v5, 4, v5
	s_addc_u32 s25, s36, s7
	s_add_i32 s38, s37, 0
	v_add_u32_e32 v2, v16, v17
	v_or3_b32 v4, v6, v5, v4
	v_mul_lo_u32 v3, v3, s4
	s_add_i32 m0, s38, 0x10000
	v_add_lshl_u32 v134, v2, v3, 1
	v_mul_u32_u24_e32 v3, 0xb00, v4
	global_load_lds_dwordx4 v132, s[24:25]
	s_add_i32 m0, s38, 0x12000
	v_add_lshl_u32 v136, v3, v2, 1
	s_add_u32 s6, s24, 0xb0000
	global_load_lds_dwordx4 v136, s[24:25]
	s_addc_u32 s7, s25, 0
	s_add_i32 m0, s38, 0x14000
	s_mul_i32 s10, s31, 0x160000
	global_load_lds_dwordx4 v132, s[6:7]
	s_add_i32 m0, s38, 0x16000
	s_mul_hi_i32 s8, s31, 0x160000
	s_add_u32 s18, s16, s10
	s_addc_u32 s19, s17, s8
	s_add_i32 s39, s38, 0x2000
	global_load_lds_dwordx4 v136, s[6:7]
	s_mov_b32 m0, s38
	s_add_u32 s6, s18, 0xb0000
	global_load_lds_dwordx4 v130, s[18:19]
	s_mov_b32 m0, s39
	s_addc_u32 s7, s19, 0
	s_add_i32 s40, s38, 0x4000
	global_load_lds_dwordx4 v134, s[18:19]
	s_mov_b32 m0, s40
	s_add_i32 s41, s38, 0x6000
	global_load_lds_dwordx4 v130, s[6:7]
	s_mov_b32 m0, s41
	v_readlane_b32 s8, v247, 42
	v_readlane_b32 s9, v247, 43
	v_readlane_b32 s10, v247, 44
	v_readlane_b32 s11, v247, 45
	s_nop 4
	global_load_lds_dwordx4 v134, s[6:7]
	v_mov_b32_e32 v133, 0
	v_mov_b32_e32 v137, v133
	v_mov_b32_e32 v131, v133
	v_mov_b32_e32 v135, v133
	s_mov_b32 s42, 0
	v_lshl_add_u64 v[8:9], s[24:25], 0, v[132:133]
	v_lshl_add_u64 v[6:7], s[24:25], 0, v[136:137]
	v_lshl_add_u64 v[4:5], s[18:19], 0, v[130:131]
	s_cmp_lg_u32 s33, 1
	v_lshl_add_u64 v[2:3], s[18:19], 0, v[134:135]
	s_cbranch_scc1 .LBB0_1826
	s_barrier
